# first seam through the XCD barrier; qk_prep token loads hoisted into one batch
# speedup vs baseline: 1.0144x; 1.0011x over previous
; #define LAS __attribute__((address_space(3)))
; __global__ void __launch_bounds__(512) mk_fwd(Params P) {
;     ...
;     unsigned char* ws = P.ws;
;     bf16_t* WB = (bf16_t*)(ws + WS_W);
;     float* SSQ = (float*)(ws + WS_SSQ);
;     bf16_t* HB = (bf16_t*)(ws + WS_HB);
;     const int G = (int)gridDim.x, bx = (int)blockIdx.x;
;     const int vcu = (G % 8 == 0) ? (bx % 8) * (G / 8) + bx / 8 : bx;
;     volatile LAS unsigned* bst = (volatile LAS unsigned*)(lds + 135168);
;     if (threadIdx.x < 2) bst[threadIdx.x] = 0u;
;     __syncthreads();
;     XcdBarrier xbar = xcd_barrier_post((unsigned*)(ws + WS_BAR), bst);
;     bool first_seam = true;
.LBB0_8:
	s_add_u32 vcc_lo, s92, 0x400000
	s_addc_u32 vcc_hi, s93, 0
	s_add_u32 s38, s92, 0xfc00000
	s_addc_u32 s39, s93, 0
	v_readlane_b32 s17, v250, 7
	s_add_u32 s94, s92, 0x39c00000
	s_mov_b32 s23, 0
	s_mov_b32 s22, s17
	s_addc_u32 s36, s93, 0
	s_lshl_b64 s[4:5], s[22:23], 9
	v_writelane_b32 v250, s4, 10
	s_load_dwordx16 s[76:91], s[0:1], 0x0
	s_load_dwordx16 s[52:67], s[0:1], 0x40
	v_writelane_b32 v250, s5, 11
	s_mov_b32 s4, s70
	s_mov_b32 s5, s23
	s_lshl_b64 s[68:69], s[4:5], 9
	v_readlane_b32 s15, v250, 6
	s_cmpk_lt_i32 s15, 0x100
	s_cselect_b64 s[8:9], -1, 0
	s_add_u32 s72, s92, 0x19c00000
	v_writelane_b32 v250, s8, 12
	s_addc_u32 s73, s93, 0
	v_lshrrev_b32_e32 v1, 20, v0
	v_writelane_b32 v250, s9, 13
	s_add_u32 s8, s92, 0x2fc00000
	s_addc_u32 s9, s93, 0
	v_writelane_b32 v250, s8, 14
	s_cmpk_lg_i32 s70, 0x100
	v_lshrrev_b32_e32 v0, 10, v0
	v_writelane_b32 v250, s9, 15
	s_cselect_b64 s[8:9], -1, 0
	v_writelane_b32 v250, s8, 16
	s_cmpk_lt_i32 s17, 0x400
	v_or_b32_e32 v0, v0, v1
	v_writelane_b32 v250, s9, 17
	s_cselect_b64 s[8:9], -1, 0
	s_add_u32 s20, s92, 0x36000000
	s_addc_u32 s21, s93, 0
	s_add_u32 s33, s92, 0x1fc00000
	v_writelane_b32 v250, s8, 18
	s_addc_u32 s24, s93, 0
	s_lshl_b32 s3, s17, 1
	v_writelane_b32 v250, s9, 19
	s_and_b32 s8, s3, 14
	s_ashr_i32 s10, s17, 7
	s_add_i32 s9, s8, s10
	s_ashr_i32 s8, s9, 3
	s_bfe_u32 s11, s17, 0x40003
	s_and_b32 s12, s9, 7
	s_ashr_i32 s9, s8, 31
	v_writelane_b32 v250, s24, 20
	s_xor_b32 s13, s11, 63
	s_lshl_b64 s[18:19], s[8:9], 14
	s_lshl_b32 s16, s13, 8
	v_writelane_b32 v250, s18, 21
	s_mul_i32 s14, s12, 0x180
	v_mov_b32_e32 v181, 0
	v_writelane_b32 v250, s19, 22
	s_add_u32 s18, s72, s14
	s_addc_u32 s19, s73, 0
	v_writelane_b32 v250, s18, 23
	s_lshl_b32 s13, s13, 2
	v_mbcnt_lo_u32_b32 v1, -1, 0
	v_writelane_b32 v250, s19, 24
	v_writelane_b32 v250, s20, 25
	s_add_u32 s18, s20, s14
	v_writelane_b32 v250, s21, 26
	s_addc_u32 s19, s21, 0
	v_writelane_b32 v250, s18, 27
	s_lshl_b32 s14, s12, 9
	v_mov_b32_e32 v203, 0x358637bd
	v_writelane_b32 v250, s19, 28
	s_add_u32 s18, s33, s14
	s_addc_u32 s19, s24, 0
	v_writelane_b32 v250, s18, 29
	s_add_i32 s13, s13, 4
	s_lshl_b32 s12, s12, 7
	v_writelane_b32 v250, s19, 30
	v_writelane_b32 v250, s13, 31
	v_writelane_b32 v250, s12, 32
	s_xor_b32 s12, s11, 47
	s_lshl_b32 s13, s12, 8
	s_lshl_b32 s12, s12, 2
	v_writelane_b32 v250, s13, 33
	s_add_i32 s12, s12, 4
	v_writelane_b32 v250, s12, 34
	s_or_b32 s12, s11, 16
	s_lshl_b32 s13, s12, 8
	s_lshl_b32 s12, s12, 2
	v_writelane_b32 v250, s13, 35
	s_add_i32 s12, s12, 4
	v_writelane_b32 v250, s12, 36
	s_lshl_b32 s12, s11, 8
	s_lshl_b32 s11, s11, 2
	s_add_i32 s11, s11, 4
	s_lshl_b32 s37, s17, 3
	s_lshl_b32 s74, s70, 3
	s_add_u32 s18, s92, 0x2e000000
	v_writelane_b32 v250, s11, 37
	s_addc_u32 s19, s93, 0
	v_writelane_b32 v250, s18, 38
	s_add_u32 s11, s92, 0x200000
	v_mov_b32_e32 v204, 0x3e2aaaab
	v_writelane_b32 v250, s19, 39
	v_writelane_b32 v250, s11, 40
	s_addc_u32 s11, s93, 0
	s_add_u32 s18, s92, 0x29c00000
	v_writelane_b32 v250, s11, 41
	s_addc_u32 s19, s93, 0
	v_writelane_b32 v250, s18, 42
	v_mov_b32_e32 v205, 1
	v_mov_b32_e32 v206, 0x42800000
	v_writelane_b32 v250, s19, 43
	s_add_u32 s18, s92, 0x20000
	s_addc_u32 s19, s93, 0
	v_writelane_b32 v250, s18, 44
	s_add_u32 s11, s92, 0x100000
	v_not_b32_e32 v207, 63
	v_writelane_b32 v250, s19, 45
	v_writelane_b32 v250, s11, 46
	s_addc_u32 s11, s93, 0
	s_waitcnt lgkmcnt(0)
	s_cmp_lg_u64 s[86:87], 0
	v_writelane_b32 v250, s11, 47
	s_cselect_b64 s[18:19], -1, 0
	v_writelane_b32 v250, s18, 48
	s_cmp_lg_u64 s[84:85], 0
	v_mbcnt_hi_u32_b32 v208, -1, v1
	v_writelane_b32 v250, s19, 49
	s_cselect_b64 s[18:19], -1, 0
	v_writelane_b32 v250, s18, 50
	v_mov_b32_e32 v209, 7
	v_mov_b32_e32 v211, 0x180
	v_writelane_b32 v250, s19, 51
	s_add_u32 s18, s92, 0x9f80000
	s_addc_u32 s19, s93, 0
	v_writelane_b32 v250, s18, 52
	v_mov_b32_e32 v212, 0xff800000
	v_mov_b32_e32 v213, 0x41b17218
	v_writelane_b32 v250, s19, 53
	s_add_u32 s18, s92, 0x6f80000
	s_addc_u32 s19, s93, 0
	v_writelane_b32 v250, s18, 54
	v_mov_b32_e32 v210, 6
	v_mov_b32_e32 v248, 8
	v_writelane_b32 v250, s19, 55
	s_add_u32 s18, s92, 0x1c80000
	s_addc_u32 s19, s93, 0
	v_writelane_b32 v250, s18, 56
	s_mov_b32 s95, 0x3f317217
	s_nop 0
	v_writelane_b32 v250, s19, 57
	s_add_u32 s18, s92, 0x1a80000
	s_addc_u32 s19, s93, 0
	v_writelane_b32 v250, s18, 58
	s_nop 1
	v_writelane_b32 v250, s19, 59
	s_add_u32 s18, s92, 0x1900000
	s_addc_u32 s19, s93, 0
	v_writelane_b32 v250, s18, 60
	s_cmp_lg_u64 s[82:83], 0
	s_nop 0
	v_writelane_b32 v250, s19, 61
	s_cselect_b64 s[18:19], -1, 0
	s_cmp_lg_u64 s[54:55], 0
	v_writelane_b32 v250, s52, 62
	s_cselect_b64 s[20:21], -1, 0
	s_cmp_lg_u64 s[52:53], 0
	v_writelane_b32 v251, s54, 0
	v_writelane_b32 v251, s55, 1
	v_writelane_b32 v251, s56, 2
	v_writelane_b32 v251, s57, 3
	v_writelane_b32 v251, s58, 4
	v_writelane_b32 v251, s59, 5
	v_writelane_b32 v251, s60, 6
	v_writelane_b32 v251, s61, 7
	v_writelane_b32 v251, s62, 8
	v_writelane_b32 v251, s63, 9
	v_writelane_b32 v251, s64, 10
	v_writelane_b32 v251, s65, 11
	v_writelane_b32 v251, s66, 12
	v_writelane_b32 v251, s67, 13
	s_cselect_b64 s[24:25], -1, 0
	s_add_u32 s11, s92, 0x17c00000
	v_writelane_b32 v251, s11, 14
	s_addc_u32 s11, s93, 0
	s_add_u32 s26, s92, 0x31c00000
	s_addc_u32 s27, s93, 0
	s_cmpk_lt_i32 s15, 0x400
	v_writelane_b32 v251, s11, 15
	s_cselect_b64 s[28:29], -1, 0
	v_writelane_b32 v251, s28, 16
	v_writelane_b32 v250, s53, 63
	s_nop 0
	v_writelane_b32 v251, s29, 17
	s_add_u32 s28, s92, 0x34000000
	s_addc_u32 s29, s93, 0
	v_writelane_b32 v251, s28, 18
	s_add_u32 s11, s92, 0x80000
	s_nop 0
	v_writelane_b32 v251, s29, 19
	v_writelane_b32 v251, s11, 20
; #define LAS __attribute__((address_space(3)))
; __device__ __forceinline__ unsigned xb_ld(unsigned* p)              { return __hip_atomic_load(p, __ATOMIC_RELAXED, __HIP_MEMORY_SCOPE_AGENT); }
; __device__ __forceinline__ unsigned xb_add(unsigned* p, unsigned v) { return __hip_atomic_fetch_add(p, v, __ATOMIC_RELAXED, __HIP_MEMORY_SCOPE_AGENT); }
; __device__ __forceinline__ unsigned xb_xcc_id() { return (unsigned)__builtin_amdgcn_s_getreg((3 << 11) | 20) & 0xFu; }
; __device__ __forceinline__ XcdBarrier xcd_barrier_post(unsigned* bar, volatile LAS unsigned* st) {
;     XcdBarrier b; b.bar = bar; b.x = xb_xcc_id(); b.st = st;
;     if (threadIdx.x == 0) (void)xb_add(&bar[XB_XCNT(b.x)], 1u);
;     return b;
; }
; __device__ __forceinline__ void xcd_barrier_complete(unsigned* bar, unsigned x, unsigned& nloc, unsigned& nx) {
;     const unsigned G = gridDim.x * gridDim.y * gridDim.z;
;     unsigned sum, cnt, mine, sp = 0u;
;     for (;;) {
;         sum = 0u; cnt = 0u; mine = 0u;
; #pragma unroll
;         for (unsigned j = 0; j < 16; ++j) { const unsigned c = xb_ld(&bar[XB_XCNT(j)]); sum += c; cnt += (c > 0u) ? 1u : 0u; mine = (j == x) ? c : mine; }
;         if (sum == G) break;
;         __builtin_amdgcn_s_sleep(1);
;         if ((++sp & 255u) == 0u) { if (xb_ld(&bar[XB_TMO])) break; if (sp > XB_SPIN_CAP) { atomicAdd(&bar[XB_TMO], 1u); break; } }
;     }
;     nloc = mine > 0u ? mine : 1u; nx = cnt > 0u ? cnt : 1u;
; }
; __global__ void __launch_bounds__(512) mk_fwd(Params P) {
;     ...
;     XcdBarrier xbar = xcd_barrier_post((unsigned*)(ws + WS_BAR), bst);
	s_addc_u32 s11, s93, 0
	v_writelane_b32 v251, s11, 21
	s_add_u32 s11, s92, 0x60000
	v_writelane_b32 v251, s11, 22
	s_addc_u32 s11, s93, 0
	v_writelane_b32 v251, s11, 23
	s_add_u32 s11, s92, 0x3c000000
	v_writelane_b32 v251, s11, 24
	s_addc_u32 s11, s93, 0
	s_ashr_i32 s52, s17, 31
	v_writelane_b32 v251, s11, 25
	s_lshr_b32 s11, s52, 29
	s_add_i32 s11, s17, s11
	s_ashr_i32 s13, s11, 3
	s_and_b32 s11, s11, -8
	s_sub_i32 s11, s17, s11
	s_ashr_i32 s14, s70, 31
	s_add_u32 s28, s92, 0x300200
	v_writelane_b32 v251, s14, 26
	s_addc_u32 s29, s93, 0
	v_writelane_b32 v251, s28, 27
	s_nop 1
	v_writelane_b32 v251, s29, 28
	s_add_u32 s28, s92, 0x300400
	s_addc_u32 s29, s93, 0
	v_writelane_b32 v251, s28, 29
	s_add_u32 s30, s92, 0x300500
	s_addc_u32 s31, s93, 0
	v_writelane_b32 v251, s29, 30
	v_writelane_b32 v251, s30, 31
	s_nop 1
	v_writelane_b32 v251, s31, 32
	s_add_u32 s30, s92, 0x300600
	s_addc_u32 s31, s93, 0
	v_writelane_b32 v251, s30, 33
	s_nop 1
	v_writelane_b32 v251, s31, 34
	s_add_u32 s30, s92, 0x300700
	s_addc_u32 s31, s93, 0
	v_writelane_b32 v251, s30, 35
	s_nop 1
	v_writelane_b32 v251, s31, 36
	s_add_u32 s30, s92, 0x300800
	s_addc_u32 s31, s93, 0
	v_writelane_b32 v251, s30, 37
	s_nop 1
	v_writelane_b32 v251, s31, 38
	s_add_u32 s30, s92, 0x300900
	s_addc_u32 s31, s93, 0
	v_writelane_b32 v251, s30, 39
	s_nop 1
	v_writelane_b32 v251, s31, 40
	s_add_u32 s30, s92, 0x300a00
	s_addc_u32 s31, s93, 0
	v_writelane_b32 v251, s30, 41
	s_nop 1
	v_writelane_b32 v251, s31, 42
	s_add_u32 s30, s92, 0x300b00
	s_addc_u32 s31, s93, 0
	v_writelane_b32 v251, s30, 43
	s_nop 1
	v_writelane_b32 v251, s31, 44
	s_add_u32 s30, s92, 0x300c00
	s_addc_u32 s31, s93, 0
	v_writelane_b32 v251, s30, 45
	s_nop 1
	v_writelane_b32 v251, s31, 46
	s_add_u32 s30, s92, 0x300d00
	s_addc_u32 s31, s93, 0
	v_writelane_b32 v251, s30, 47
	s_nop 1
	v_writelane_b32 v251, s31, 48
	s_add_u32 s30, s92, 0x300e00
	s_addc_u32 s31, s93, 0
	v_writelane_b32 v251, s30, 49
	s_nop 1
	v_writelane_b32 v251, s31, 50
	s_add_u32 s30, s92, 0x300f00
	s_addc_u32 s31, s93, 0
	v_writelane_b32 v251, s30, 51
	s_nop 1
	v_writelane_b32 v251, s31, 52
	s_add_u32 s30, s92, 0x301000
	s_addc_u32 s31, s93, 0
	v_writelane_b32 v251, s30, 53
	s_nop 1
	v_writelane_b32 v251, s31, 54
	s_add_u32 s30, s92, 0x301100
	s_addc_u32 s31, s93, 0
	v_writelane_b32 v251, s30, 55
	s_nop 1
	v_writelane_b32 v251, s31, 56
	s_add_u32 s30, s92, 0x301200
	s_addc_u32 s31, s93, 0
	v_writelane_b32 v251, s30, 57
	s_nop 1
	v_writelane_b32 v251, s31, 58
	s_add_u32 s30, s92, 0x301300
	s_addc_u32 s31, s93, 0
	v_writelane_b32 v251, s30, 59
	s_cmp_eq_u32 s2, 15
	s_nop 0
	v_writelane_b32 v251, s31, 60
	s_cselect_b64 s[30:31], -1, 0
	v_writelane_b32 v251, s30, 61
	s_cmp_eq_u32 s2, 14
	s_nop 0
	v_writelane_b32 v251, s31, 62
	s_cselect_b64 s[30:31], -1, 0
	v_writelane_b32 v251, s30, 63
	s_cmp_eq_u32 s2, 13
	s_nop 0
	v_writelane_b32 v252, s31, 0
	s_cselect_b64 s[30:31], -1, 0
	v_writelane_b32 v252, s30, 1
	s_cmp_eq_u32 s2, 12
	s_nop 0
	v_writelane_b32 v252, s31, 2
	s_cselect_b64 s[30:31], -1, 0
	v_writelane_b32 v252, s30, 3
	s_cmp_eq_u32 s2, 11
	s_nop 0
	v_writelane_b32 v252, s31, 4
	s_cselect_b64 s[30:31], -1, 0
	v_writelane_b32 v252, s30, 5
	s_cmp_eq_u32 s2, 10
	s_nop 0
	v_writelane_b32 v252, s31, 6
	s_cselect_b64 s[30:31], -1, 0
	v_writelane_b32 v252, s30, 7
	s_cmp_eq_u32 s2, 9
	s_nop 0
	v_writelane_b32 v252, s31, 8
	s_cselect_b64 s[30:31], -1, 0
	v_writelane_b32 v252, s30, 9
	s_cmp_eq_u32 s2, 8
	s_nop 0
	v_writelane_b32 v252, s31, 10
	s_cselect_b64 s[30:31], -1, 0
	v_writelane_b32 v252, s30, 11
	s_cmp_eq_u32 s2, 7
	s_nop 0
	v_writelane_b32 v252, s31, 12
	s_cselect_b64 s[30:31], -1, 0
	v_writelane_b32 v252, s30, 13
	s_cmp_eq_u32 s2, 6
	s_nop 0
	v_writelane_b32 v252, s31, 14
	s_cselect_b64 s[30:31], -1, 0
	v_writelane_b32 v252, s30, 15
	s_cmp_eq_u32 s2, 5
	s_nop 0
	v_writelane_b32 v252, s31, 16
	s_cselect_b64 s[30:31], -1, 0
	v_writelane_b32 v252, s30, 17
	s_cmp_eq_u32 s2, 4
	s_nop 0
	v_writelane_b32 v252, s31, 18
	s_cselect_b64 s[30:31], -1, 0
	v_writelane_b32 v252, s30, 19
	s_cmp_eq_u32 s2, 3
	s_nop 0
	v_writelane_b32 v252, s31, 20
	s_cselect_b64 s[30:31], -1, 0
	v_writelane_b32 v252, s30, 21
	s_cmp_eq_u32 s2, 2
	s_nop 0
	v_writelane_b32 v252, s31, 22
	s_cselect_b64 s[30:31], -1, 0
	v_writelane_b32 v252, s30, 23
	s_cmp_eq_u32 s2, 1
	s_nop 0
	v_writelane_b32 v252, s31, 24
	s_cselect_b64 s[30:31], -1, 0
	v_writelane_b32 v252, s30, 25
	s_cmp_eq_u32 s2, 0
	s_nop 0
	v_writelane_b32 v252, s31, 26
	s_cselect_b64 s[30:31], -1, 0
	s_lshl_b32 s2, s2, 8
	s_add_u32 s2, s6, s2
	v_writelane_b32 v252, s30, 27
	s_addc_u32 s6, s7, 0
	s_nop 0
	v_writelane_b32 v252, s31, 28
	s_add_u32 s30, s2, 0x1400
	s_addc_u32 s31, s6, 0
	v_writelane_b32 v252, s30, 29
	s_nop 1
	v_writelane_b32 v252, s31, 30
	s_add_u32 s30, s2, 0x2400
	s_addc_u32 s31, s6, 0
	v_writelane_b32 v252, s30, 31
	s_add_u32 s6, s92, 0x303400
	s_addc_u32 s7, s93, 0
	v_writelane_b32 v252, s31, 32
	v_writelane_b32 v252, s6, 33
	s_nop 1
	v_writelane_b32 v252, s7, 34
	s_add_u32 s6, s92, 0x303500
	s_addc_u32 s7, s93, 0
	v_writelane_b32 v252, s6, 35
	s_lshr_b32 s2, s11, 31
	s_nop 0
	v_writelane_b32 v252, s7, 36
	v_writelane_b32 v252, s11, 37
	v_writelane_b32 v252, s2, 38
	s_lshl_b32 s2, s17, 12
	v_writelane_b32 v252, s2, 39
	s_lshl_b32 s2, s15, 7
	v_writelane_b32 v252, s2, 40
	s_lshl_b32 s2, s70, 7
	v_writelane_b32 v252, s2, 41
	s_lshl_b32 s2, s15, 6
	v_writelane_b32 v252, s2, 42
	s_lshl_b32 s2, s70, 6
	v_writelane_b32 v252, s2, 43
	s_lshl_b32 s2, s17, 9
	s_lshl_b32 s11, s70, 12
	v_writelane_b32 v252, s2, 44
	s_lshl_b32 s2, s70, 9
	s_add_u32 s6, s92, 0x19d82000
	v_writelane_b32 v252, s2, 45
	s_addc_u32 s7, s93, 0
; #define LAS __attribute__((address_space(3)))
; __global__ void __launch_bounds__(512) mk_fwd(Params P) {
;     ...
;     unsigned char* ws = P.ws;
;     bf16_t* WB = (bf16_t*)(ws + WS_W);
;     float* SSQ = (float*)(ws + WS_SSQ);
;     bf16_t* HB = (bf16_t*)(ws + WS_HB);
;     const int G = (int)gridDim.x, bx = (int)blockIdx.x;
;     const int vcu = (G % 8 == 0) ? (bx % 8) * (G / 8) + bx / 8 : bx;
;     volatile LAS unsigned* bst = (volatile LAS unsigned*)(lds + 135168);
;     if (threadIdx.x < 2) bst[threadIdx.x] = 0u;
;     __syncthreads();
;     XcdBarrier xbar = xcd_barrier_post((unsigned*)(ws + WS_BAR), bst);
;     bool first_seam = true;
;     ...
;     for (int ph = P.ph_lo; ph < P.ph_hi; ++ph) {
	v_writelane_b32 v252, s6, 46
	s_add_u32 s2, s92, 0x19d81000
	s_nop 0
	v_writelane_b32 v252, s7, 47
	v_writelane_b32 v252, s2, 48
	s_addc_u32 s2, s93, 0
	s_add_i32 s3, s3, s10
	s_and_b32 s6, s3, 7
	v_writelane_b32 v252, s2, 49
	s_lshl_b32 s7, s6, 9
	s_lshl_b64 s[2:3], s[8:9], 26
	s_or_b32 s2, s2, s7
	s_xor_b32 s7, s17, 63
	s_add_u32 s2, s2, 0x1fc40100
	v_writelane_b32 v252, s7, 50
	s_addc_u32 s3, s3, 0
	v_writelane_b32 v252, s2, 51
	s_mulk_i32 s6, 0x180
	s_nop 0
	v_writelane_b32 v252, s3, 52
	s_mul_i32 s3, s8, 0x3000000
	s_or_b32 s3, s3, s6
	s_mul_hi_i32 s2, s8, 0x3000000
	s_add_u32 s6, s3, 0x36030000
	s_addc_u32 s7, s2, 0
	v_writelane_b32 v252, s6, 53
	s_add_i32 s2, s16, 0x100
	s_ashr_i32 s75, s74, 31
	v_writelane_b32 v252, s7, 54
	v_writelane_b32 v252, s16, 55
	v_writelane_b32 v252, s2, 56
	s_add_i32 s2, s12, 0x1100
	v_writelane_b32 v252, s2, 57
	v_writelane_b32 v252, s12, 58
	s_add_i32 s2, s12, 0x100
	v_writelane_b32 v252, s2, 59
	s_lshl_b64 s[2:3], s[74:75], 12
	s_lshl_b64 s[96:97], s[74:75], 2
	v_writelane_b32 v252, s2, 60
	s_mov_b64 s[8:9], 0x80
	s_nop 0
	v_writelane_b32 v252, s3, 61
	s_add_u32 s2, s92, 0x29c00800
	s_addc_u32 s3, s93, 0
	v_writelane_b32 v252, s2, 62
	s_nop 1
	v_writelane_b32 v252, s3, 63
	s_lshl_b32 s2, s17, 5
	v_writelane_b32 v253, s2, 0
	s_lshl_b32 s2, s70, 5
	v_writelane_b32 v253, s2, 1
	s_lshl_b32 s2, s17, 8
	v_writelane_b32 v253, s2, 2
	s_lshl_b32 s2, s70, 8
	v_writelane_b32 v253, s2, 3
	s_add_u32 s2, s92, 0xc0000
	s_addc_u32 s3, s93, 0
	v_writelane_b32 v253, s2, 4
	s_nop 1
	v_writelane_b32 v253, s3, 5
	s_lshl_b64 s[2:3], s[22:23], 11
	s_add_u32 s2, s92, s2
	s_addc_u32 s3, s93, s3
	s_add_u32 s6, s2, 0x20000
	s_addc_u32 s7, s3, 0
	v_writelane_b32 v253, s6, 6
	s_nop 1
	v_writelane_b32 v253, s7, 7
	s_lshl_b64 s[6:7], s[4:5], 11
	v_writelane_b32 v253, s6, 8
	s_add_u32 s2, s2, 0x100000
	s_addc_u32 s3, s3, 0
	v_writelane_b32 v253, s7, 9
	v_writelane_b32 v253, s2, 10
	s_nop 1
	v_writelane_b32 v253, s3, 11
	v_writelane_b32 v253, s37, 12
	s_add_i32 s2, s37, 0xffffd020
	v_writelane_b32 v253, s2, 13
	s_lshl_b32 s2, s17, 4
	s_add_i32 s3, s2, 0x1b040
	v_writelane_b32 v253, s3, 14
	s_lshl_b32 s3, s70, 4
	s_add_u32 s6, s82, 0x2000
	v_writelane_b32 v253, s3, 15
	s_addc_u32 s7, s83, 0
	v_writelane_b32 v253, s6, 16
	s_add_i32 s3, s2, 0x1e840
	s_add_i32 s2, s2, 64
	v_writelane_b32 v253, s7, 17
	v_writelane_b32 v253, s3, 18
	v_writelane_b32 v253, s2, 19
	s_add_u32 s2, s82, 32
	s_addc_u32 s3, s83, 0
	v_writelane_b32 v253, s2, 20
	s_nop 1
	v_writelane_b32 v253, s3, 21
	s_add_u32 s2, s76, 0x1000
	s_addc_u32 s3, s77, 0
	v_writelane_b32 v253, s2, 22
	s_nop 1
	v_writelane_b32 v253, s3, 23
	s_lshl_b64 s[2:3], s[74:75], 13
	v_writelane_b32 v253, s2, 24
	s_mov_b32 s75, s36
	s_nop 0
	v_writelane_b32 v253, s3, 25
	s_lshl_b64 s[2:3], s[22:23], 13
	s_add_u32 s2, s78, s2
	v_writelane_b32 v253, s76, 26
	s_addc_u32 s3, s79, s3
	s_nop 0
	v_writelane_b32 v253, s77, 27
	v_writelane_b32 v253, s78, 28
	v_writelane_b32 v253, s79, 29
	v_writelane_b32 v253, s80, 30
	v_writelane_b32 v253, s81, 31
	v_writelane_b32 v253, s82, 32
	v_writelane_b32 v253, s83, 33
	v_writelane_b32 v253, s84, 34
	v_writelane_b32 v253, s85, 35
	v_writelane_b32 v253, s86, 36
	v_writelane_b32 v253, s87, 37
	v_writelane_b32 v253, s88, 38
	v_writelane_b32 v253, s89, 39
	v_writelane_b32 v253, s90, 40
	v_writelane_b32 v253, s91, 41
	v_writelane_b32 v253, s2, 42
	s_mov_b64 s[76:77], s[38:39]
	s_load_dwordx16 s[36:51], s[0:1], 0x80
	v_writelane_b32 v253, s3, 43
	s_load_dword s3, s[0:1], 0xe8
	s_mul_i32 s2, s71, s70
	s_mov_b32 s0, s74
	s_mov_b64 s[80:81], s[18:19]
	s_mov_b64 s[82:83], s[20:21]
	s_waitcnt lgkmcnt(0)
	s_mul_i32 s2, s2, s3
	v_writelane_b32 v253, s2, 44
	s_movk_i32 s2, 0x3ff
	v_and_or_b32 v0, v0, s2, v202
	s_lshl_b64 s[2:3], s[4:5], 13
	v_writelane_b32 v253, s2, 45
	s_mov_b64 s[84:85], s[24:25]
	s_mov_b64 s[86:87], s[26:27]
	v_writelane_b32 v253, s3, 46
	s_lshl_b64 s[2:3], s[22:23], 12
	s_add_u32 s2, s92, s2
	s_addc_u32 s3, s93, s3
	s_add_u32 s2, s2, 0x17c00000
	s_addc_u32 s3, s3, 0
	v_writelane_b32 v253, s2, 47
	s_mov_b32 s22, s11
	s_mov_b32 s89, s13
	v_writelane_b32 v253, s3, 48
	s_mul_i32 s2, s70, 0x6000
	s_mul_hi_i32 s3, s74, 0xc00
	v_writelane_b32 v253, s2, 49
	s_mov_b32 s71, 0x800000
	s_movk_i32 s78, 0x1000
	v_writelane_b32 v253, s3, 50
	s_mul_i32 s2, s70, 0x4400
	s_mul_hi_i32 s3, s74, 0x880
	v_writelane_b32 v253, s2, 51
	s_mov_b32 s88, 0x7f800000
	s_movk_i32 s79, 0x5100
	v_writelane_b32 v253, s3, 52
	s_lshl_b64 s[2:3], s[4:5], 12
	v_writelane_b32 v253, s2, 53
	s_mov_b64 s[18:19], 0x180000
	s_nop 0
	v_writelane_b32 v253, s3, 54
	s_add_i32 s2, 0, 0x18800
	v_writelane_b32 v253, s2, 55
	s_add_i32 s2, 0, 0x11000
	v_writelane_b32 v253, s2, 56
	s_add_i32 s2, 0, 0x16000
	v_writelane_b32 v253, s2, 57
	s_add_i32 s2, 0, 0x13800
	v_writelane_b32 v253, s2, 58
	s_add_i32 s2, 0, 0x19000
	v_writelane_b32 v253, s2, 59
	s_add_i32 s2, 0, 0x16800
	v_writelane_b32 v253, s2, 60
	s_add_i32 s2, 0, 0x19a00
	v_writelane_b32 v253, s2, 61
	s_add_i32 s2, 0, 0x19800
	v_writelane_b32 v253, s2, 62
	s_add_i32 s2, 0, 0x21000
	v_writelane_b32 v253, s2, 63
	s_add_i32 s2, 0, 0x21004
	v_writelane_b32 v254, s2, 0
	v_cmp_eq_u32_e64 s[2:3], 0, v0
	s_nop 1
	v_writelane_b32 v254, s2, 1
	s_nop 1
	v_writelane_b32 v254, s3, 2
	s_mov_b64 s[2:3], 0
	v_writelane_b32 v254, s2, 3
	s_nop 1
	v_writelane_b32 v254, s3, 4
	v_writelane_b32 v254, s36, 5
	s_nop 1
	v_writelane_b32 v254, s37, 6
	v_writelane_b32 v254, s38, 7
	v_writelane_b32 v254, s39, 8
	v_writelane_b32 v254, s40, 9
	v_writelane_b32 v254, s41, 10
	v_writelane_b32 v254, s42, 11
	v_writelane_b32 v254, s43, 12
	v_writelane_b32 v254, s44, 13
	v_writelane_b32 v254, s45, 14
	v_writelane_b32 v254, s46, 15
	v_writelane_b32 v254, s47, 16
	v_writelane_b32 v254, s48, 17
	v_writelane_b32 v254, s49, 18
	v_writelane_b32 v254, s50, 19
	v_writelane_b32 v254, s51, 20
	v_writelane_b32 v254, vcc_lo, 21
	s_mov_b32 s48, s33
	v_readlane_b32 s46, v250, 14
	v_writelane_b32 v254, vcc_hi, 22
	v_writelane_b32 v254, s76, 23
	v_readlane_b32 s44, v250, 21
	v_readlane_b32 s36, v250, 10
	v_writelane_b32 v254, s77, 24
	v_writelane_b32 v254, s0, 25
	v_readlane_b32 s47, v250, 15
	v_readlane_b32 s49, v250, 31
	v_writelane_b32 v254, s1, 26
	v_writelane_b32 v254, s52, 27
	v_writelane_b32 v254, s22, 28
	v_writelane_b32 v254, s96, 29
	v_readlane_b32 s45, v250, 22
	v_readlane_b32 s37, v250, 11
	v_writelane_b32 v254, s97, 30
	v_writelane_b32 v254, s94, 31
	v_writelane_b32 v254, s75, 32
	v_writelane_b32 v254, s68, 33
	s_mov_b64 s[50:51], s[34:35]
	s_nop 0
	v_writelane_b32 v254, s69, 34
	v_writelane_b32 v254, s72, 35
	s_nop 1
	v_writelane_b32 v254, s73, 36
	v_writelane_b32 v254, s48, 37
	v_writelane_b32 v254, s80, 38
	s_nop 1
	v_writelane_b32 v254, s81, 39
	v_writelane_b32 v254, s82, 40
	s_nop 1
	v_writelane_b32 v254, s83, 41
	v_writelane_b32 v254, s84, 42
	s_nop 1
	v_writelane_b32 v254, s85, 43
	v_writelane_b32 v254, s86, 44
	s_nop 1
	v_writelane_b32 v254, s87, 45
	v_writelane_b32 v254, s89, 46
	s_branch .LBB0_13

; __device__ __forceinline__ float bf2f(unsigned short h) { return __uint_as_float(((unsigned)h) << 16); }
; __device__ __forceinline__ unsigned short f2bf(float f) { return (unsigned short)(cvt_pk_bf16(f, 0.f) & 0xffffu); }
; __device__ __forceinline__ void pass_qk_prep(const Params& P) {
;     ...
;     for (int t = GWAVE_ID; t < T_TOK; t += GWAVES) {
;         float sn, cs; sincos_red((float)pos[t] * invf, sn, cs);
;         const float kpe = bf2f(ZB[(size_t)t * ZB_LD + 1024 + lane]);
; #pragma unroll
;         for (int h = 0; h < 8; ++h) {
;             bf16_t* q = QB + (size_t)t * 1536 + h * 192;
;             float a0 = bf2f(q[lane]), a1 = bf2f(q[64 + lane]), a2 = bf2f(q[128 + lane]);
;             float rs = rsqrtf(wave_sum(a0 * a0 + a1 * a1 + a2 * a2) * (1.f / 192.f) + EPS);
;             a0 *= rs * qn0; a1 *= rs * qn1; a2 *= rs * qn2;
;             float ot = __shfl_xor(a2, 32);
;             float r2 = lane < 32 ? a2 * cs - ot * sn : a2 * cs + ot * sn;
;             q[lane] = f2bf(a0 * QSC); q[64 + lane] = f2bf(a1 * QSC); q[128 + lane] = f2bf(r2 * QSC);
;             const bf16_t* kv = KVR + (size_t)t * 2048 + h * 256;
;             float b0 = bf2f(kv[lane]), b1 = bf2f(kv[64 + lane]), b2 = kpe;
;             rs = rsqrtf(wave_sum(b0 * b0 + b1 * b1 + b2 * b2) * (1.f / 192.f) + EPS);
;             b0 *= rs * kn0; b1 *= rs * kn1; b2 *= rs * kn2;
;             ot = __shfl_xor(b2, 32);
;             r2 = lane < 32 ? b2 * cs - ot * sn : b2 * cs + ot * sn;
;             bf16_t* k = KB + (size_t)t * 1536 + h * 192;
;             k[lane] = f2bf(b0); k[64 + lane] = f2bf(b1); k[128 + lane] = f2bf(r2);
;         }
.LBB0_202:
	global_load_dword v1, v[2:3], off
	s_waitcnt lgkmcnt(0)
	v_lshl_add_u64 v[18:19], v[6:7], 0, v[180:181]
	s_mov_b32 s0, 0x19c00000
	v_lshl_add_u64 v[12:13], v[8:9], 0, v[180:181]
	v_add_u32_e32 v0, s74, v0
	v_lshl_add_u64 v[2:3], v[2:3], 0, s[96:97]
	v_lshl_add_u64 v[6:7], v[6:7], 0, s[6:7]
	v_lshl_add_u64 v[8:9], v[8:9], 0, s[10:11]
	s_waitcnt vmcnt(0)
	v_cvt_f32_i32_e32 v1, v1
	v_mul_f32_e32 v1, v36, v1
	v_mul_f32_e32 v10, 0.15915494, v1
	v_rndne_f32_e32 v10, v10
	v_fmac_f32_e32 v1, 0xc0c90000, v10
	v_fmac_f32_e32 v1, 0xbafdaa22, v10
	v_add_co_u32_e64 v10, s[0:1], s0, v18
	v_mul_f32_e32 v1, 0.15915494, v1
	s_nop 0
	v_addc_co_u32_e64 v11, s[0:1], 0, v19, s[0:1]
	v_lshl_add_u64 v[100:101], v[4:5], 0, v[180:181]
	v_add_co_u32_e64 v100, s[0:1], s14, v100
	s_nop 1
	v_addc_co_u32_e64 v101, s[0:1], 0, v101, s[0:1]
	global_load_ushort v56, v[10:11], off offset:128
	global_load_ushort v57, v[10:11], off
	global_load_ushort v58, v[10:11], off offset:256
	global_load_ushort v59, v[12:13], off
	global_load_ushort v60, v[100:101], off
	global_load_ushort v61, v[100:101], off offset:128
	global_load_ushort v62, v[10:11], off offset:512
	global_load_ushort v63, v[10:11], off offset:384
	global_load_ushort v64, v[10:11], off offset:640
	global_load_ushort v65, v[100:101], off offset:512
	global_load_ushort v66, v[100:101], off offset:640
	global_load_ushort v67, v[10:11], off offset:896
	global_load_ushort v68, v[10:11], off offset:768
	global_load_ushort v69, v[10:11], off offset:1024
	global_load_ushort v70, v[100:101], off offset:1024
	global_load_ushort v71, v[100:101], off offset:1152
	global_load_ushort v72, v[10:11], off offset:1280
	global_load_ushort v73, v[10:11], off offset:1152
	global_load_ushort v74, v[10:11], off offset:1408
	global_load_ushort v75, v[100:101], off offset:1536
	global_load_ushort v76, v[100:101], off offset:1664
	global_load_ushort v77, v[10:11], off offset:1664
	global_load_ushort v78, v[10:11], off offset:1536
	global_load_ushort v79, v[10:11], off offset:1792
	global_load_ushort v80, v[100:101], off offset:2048
	global_load_ushort v81, v[100:101], off offset:2176
	global_load_ushort v82, v[10:11], off offset:2048
	global_load_ushort v83, v[10:11], off offset:1920
	global_load_ushort v84, v[10:11], off offset:2176
	global_load_ushort v85, v[100:101], off offset:2560
	global_load_ushort v86, v[100:101], off offset:2688
	global_load_ushort v87, v[10:11], off offset:2432
	global_load_ushort v88, v[10:11], off offset:2304
	global_load_ushort v89, v[10:11], off offset:2560
	global_load_ushort v90, v[100:101], off offset:3072
	global_load_ushort v91, v[100:101], off offset:3200
	global_load_ushort v92, v[10:11], off offset:2816
	global_load_ushort v93, v[10:11], off offset:2688
	global_load_ushort v94, v[10:11], off offset:2944
	global_load_ushort v95, v[100:101], off offset:3584
	global_load_ushort v96, v[100:101], off offset:3712
	s_waitcnt vmcnt(0)
	v_lshl_add_u64 v[50:51], v[6:7], 0, v[48:49]
	global_load_dword v52, v[50:51], off
	v_lshl_add_u64 v[50:51], v[4:5], 0, v[54:55]
	global_load_dword v53, v[50:51], off
	v_mov_b32_e32 v14, v56
	v_sin_f32_e32 v43, v1
	v_cos_f32_e32 v1, v1
	v_lshlrev_b32_e32 v20, 16, v14
	v_mov_b32_e32 v14, v57
	v_mov_b32_e32 v15, v58
	v_mov_b32_e32 v24, v59
	v_lshlrev_b32_e32 v14, 16, v14
	v_lshlrev_b32_e32 v15, 16, v15
	v_pk_mul_f32 v[16:17], v[14:15], v[14:15]
	s_nop 0
	v_fma_f32 v16, v20, v20, v16
	v_add_f32_e32 v16, v16, v17
	s_nop 1
	v_mov_b32_dpp v17, v16 quad_perm:[1,0,3,2] row_mask:0xf bank_mask:0xf
	s_waitcnt lgkmcnt(0)
	v_add_f32_e32 v16, v16, v17
	s_nop 1
	v_mov_b32_dpp v17, v16 quad_perm:[2,3,0,1] row_mask:0xf bank_mask:0xf
	s_waitcnt lgkmcnt(0)
	v_add_f32_e32 v16, v16, v17
	s_nop 1
	v_mov_b32_dpp v17, v16 row_half_mirror row_mask:0xf bank_mask:0xf
	s_waitcnt lgkmcnt(0)
	v_add_f32_e32 v16, v16, v17
	s_nop 1
	v_mov_b32_dpp v17, v16 row_mirror row_mask:0xf bank_mask:0xf
	s_waitcnt lgkmcnt(0)
	v_add_f32_e32 v16, v16, v17
	v_mov_b32_e32 v17, v16
	s_nop 1
	v_permlane16_swap_b32 v16, v17
	s_waitcnt lgkmcnt(0)
	v_add_f32_e32 v16, v16, v17
	v_mov_b32_e32 v17, v16
	s_nop 1
	v_permlane32_swap_b32 v16, v17
	s_waitcnt lgkmcnt(0)
	v_add_f32_e32 v16, v16, v17
	v_fmamk_f32 v16, v16, 0x3baaaaab, v203
	v_cmp_gt_f32_e64 s[0:1], s71, v16
	v_mul_f32_e32 v17, 0x4b800000, v16
	s_nop 0
	v_cndmask_b32_e64 v16, v16, v17, s[0:1]
	v_rsq_f32_e32 v16, v16
	s_nop 0
	v_mul_f32_e32 v17, 0x45800000, v16
	v_cndmask_b32_e64 v16, v16, v17, s[0:1]
	v_mul_f32_e32 v17, v30, v16
	v_mul_f32_e32 v14, v17, v14
	v_mul_f32_e32 v17, v31, v16
	v_mul_f32_e32 v16, v34, v16
	v_mul_f32_e32 v15, v16, v15
	ds_bpermute_b32 v16, v42, v15
	v_mul_f32_e32 v17, v17, v20
	v_mul_f32_e32 v12, 0x3dd53b94, v17
	v_cvt_pk_bf16_f32 v12, v12, s0
	global_store_short v[10:11], v12, off offset:128
	s_waitcnt lgkmcnt(0)
	v_mul_f32_e32 v16, v43, v16
	v_cndmask_b32_e64 v16, v16, -v16, vcc
	v_fmac_f32_e32 v16, v1, v15
	v_mul_f32_e32 v12, 0x3dd53b94, v16
	v_cvt_pk_bf16_f32 v12, v12, s0
	v_mul_f32_e32 v14, 0x3dd53b94, v14
	global_store_short v[10:11], v12, off offset:256
	v_lshl_add_u64 v[12:13], v[4:5], 0, v[180:181]
	v_cvt_pk_bf16_f32 v14, v14, s0
	v_add_co_u32_e64 v12, s[0:1], s14, v12
	global_store_short v[10:11], v14, off
	s_nop 0
	v_addc_co_u32_e64 v13, s[0:1], 0, v13, s[0:1]
	v_mov_b32_e32 v14, v60
	v_mov_b32_e32 v15, v61
	v_lshl_add_u64 v[4:5], v[4:5], 0, s[2:3]
	v_lshlrev_b32_e32 v20, 16, v14
	v_mov_b32_e32 v14, v62
	v_lshlrev_b32_e32 v21, 16, v15
	v_pk_mul_f32 v[22:23], v[20:21], v[20:21]
	v_lshlrev_b32_e32 v25, 16, v14
	v_mov_b32_e32 v14, v63
	v_mov_b32_e32 v15, v64
	v_add_f32_e32 v22, v22, v23
	v_lshlrev_b32_e32 v14, 16, v14
	v_lshlrev_b32_e32 v15, 16, v15
	v_pk_mul_f32 v[16:17], v[14:15], v[14:15]
	s_nop 0
	v_fma_f32 v16, v25, v25, v16
	v_add_f32_e32 v16, v16, v17
	s_nop 1
	v_mov_b32_dpp v17, v16 quad_perm:[1,0,3,2] row_mask:0xf bank_mask:0xf
	s_waitcnt lgkmcnt(0)
; __device__ __forceinline__ float bf2f(unsigned short h) { return __uint_as_float(((unsigned)h) << 16); }
; __device__ __forceinline__ unsigned short f2bf(float f) { return (unsigned short)(cvt_pk_bf16(f, 0.f) & 0xffffu); }
; __device__ __forceinline__ void pass_qk_prep(const Params& P) {
;     ...
;         for (int h = 0; h < 8; ++h) {
;             bf16_t* q = QB + (size_t)t * 1536 + h * 192;
;             float a0 = bf2f(q[lane]), a1 = bf2f(q[64 + lane]), a2 = bf2f(q[128 + lane]);
;             float rs = rsqrtf(wave_sum(a0 * a0 + a1 * a1 + a2 * a2) * (1.f / 192.f) + EPS);
;             a0 *= rs * qn0; a1 *= rs * qn1; a2 *= rs * qn2;
;             float ot = __shfl_xor(a2, 32);
;             float r2 = lane < 32 ? a2 * cs - ot * sn : a2 * cs + ot * sn;
;             q[lane] = f2bf(a0 * QSC); q[64 + lane] = f2bf(a1 * QSC); q[128 + lane] = f2bf(r2 * QSC);
;             const bf16_t* kv = KVR + (size_t)t * 2048 + h * 256;
;             float b0 = bf2f(kv[lane]), b1 = bf2f(kv[64 + lane]), b2 = kpe;
;             rs = rsqrtf(wave_sum(b0 * b0 + b1 * b1 + b2 * b2) * (1.f / 192.f) + EPS);
;             b0 *= rs * kn0; b1 *= rs * kn1; b2 *= rs * kn2;
;             ot = __shfl_xor(b2, 32);
;             r2 = lane < 32 ? b2 * cs - ot * sn : b2 * cs + ot * sn;
;             bf16_t* k = KB + (size_t)t * 1536 + h * 192;
;             k[lane] = f2bf(b0); k[64 + lane] = f2bf(b1); k[128 + lane] = f2bf(r2);
	v_add_f32_e32 v16, v16, v17
	s_nop 1
	v_mov_b32_dpp v17, v16 quad_perm:[2,3,0,1] row_mask:0xf bank_mask:0xf
	s_waitcnt lgkmcnt(0)
	v_add_f32_e32 v16, v16, v17
	s_nop 1
	v_mov_b32_dpp v17, v16 row_half_mirror row_mask:0xf bank_mask:0xf
	s_waitcnt lgkmcnt(0)
	v_add_f32_e32 v16, v16, v17
	s_nop 1
	v_mov_b32_dpp v17, v16 row_mirror row_mask:0xf bank_mask:0xf
	s_waitcnt lgkmcnt(0)
	v_add_f32_e32 v16, v16, v17
	v_mov_b32_e32 v17, v16
	s_nop 1
	v_permlane16_swap_b32 v16, v17
	s_waitcnt lgkmcnt(0)
	v_add_f32_e32 v16, v16, v17
	v_mov_b32_e32 v17, v16
	s_nop 1
	v_permlane32_swap_b32 v16, v17
	s_waitcnt lgkmcnt(0)
	v_add_f32_e32 v16, v16, v17
	v_fmamk_f32 v16, v16, 0x3baaaaab, v203
	v_cmp_gt_f32_e64 s[0:1], s71, v16
	v_mul_f32_e32 v17, 0x4b800000, v16
	s_nop 0
	v_cndmask_b32_e64 v16, v16, v17, s[0:1]
	v_rsq_f32_e32 v16, v16
	s_nop 0
	v_mul_f32_e32 v17, 0x45800000, v16
	v_cndmask_b32_e64 v16, v16, v17, s[0:1]
	v_mul_f32_e32 v17, v30, v16
	v_mul_f32_e32 v14, v17, v14
	v_mul_f32_e32 v17, v31, v16
	v_mul_f32_e32 v16, v34, v16
	v_mul_f32_e32 v15, v16, v15
	ds_bpermute_b32 v16, v42, v15
	v_mul_f32_e32 v14, 0x3dd53b94, v14
	v_mul_f32_e32 v17, v17, v25
	v_cvt_pk_bf16_f32 v14, v14, s0
	global_store_short v[10:11], v14, off offset:384
	s_waitcnt lgkmcnt(0)
	v_mul_f32_e32 v16, v43, v16
	v_cndmask_b32_e64 v16, v16, -v16, vcc
	v_mul_f32_e32 v14, 0x3dd53b94, v17
	v_fmac_f32_e32 v16, v1, v15
	v_cvt_pk_bf16_f32 v14, v14, s0
	global_store_short v[10:11], v14, off offset:512
	v_mul_f32_e32 v14, 0x3dd53b94, v16
	v_cvt_pk_bf16_f32 v14, v14, s0
	global_store_short v[10:11], v14, off offset:640
	v_mov_b32_e32 v14, v65
	v_lshlrev_b32_e32 v15, 16, v14
	v_lshlrev_b32_e32 v14, 16, v24
	v_pk_mul_f32 v[16:17], v[14:15], v[14:15]
	s_nop 0
	v_add_f32_e32 v22, v16, v22
	s_nop 1
	v_mov_b32_dpp v23, v22 quad_perm:[1,0,3,2] row_mask:0xf bank_mask:0xf
	v_mov_b32_e32 v27, v17
	s_waitcnt lgkmcnt(0)
	v_add_f32_e32 v22, v22, v23
	s_nop 1
	v_mov_b32_dpp v23, v22 quad_perm:[2,3,0,1] row_mask:0xf bank_mask:0xf
	s_waitcnt lgkmcnt(0)
	v_add_f32_e32 v22, v22, v23
	s_nop 1
	v_mov_b32_dpp v23, v22 row_half_mirror row_mask:0xf bank_mask:0xf
	s_waitcnt lgkmcnt(0)
	v_add_f32_e32 v22, v22, v23
	s_nop 1
	v_mov_b32_dpp v23, v22 row_mirror row_mask:0xf bank_mask:0xf
	s_waitcnt lgkmcnt(0)
	v_add_f32_e32 v22, v22, v23
	v_mov_b32_e32 v23, v22
	s_nop 1
	v_permlane16_swap_b32 v22, v23
	s_waitcnt lgkmcnt(0)
	v_add_f32_e32 v22, v22, v23
	v_mov_b32_e32 v23, v22
	s_nop 1
	v_permlane32_swap_b32 v22, v23
	s_waitcnt lgkmcnt(0)
	v_add_f32_e32 v22, v22, v23
	v_fmamk_f32 v22, v22, 0x3baaaaab, v203
	v_cmp_gt_f32_e64 s[0:1], s71, v22
	v_mul_f32_e32 v23, 0x4b800000, v22
	s_nop 0
	v_cndmask_b32_e64 v22, v22, v23, s[0:1]
	v_rsq_f32_e32 v22, v22
	s_nop 0
	v_mul_f32_e32 v23, 0x45800000, v22
	v_cndmask_b32_e64 v22, v22, v23, s[0:1]
	v_mul_f32_e32 v23, v35, v22
	v_mul_f32_e32 v20, v23, v20
	v_mul_f32_e32 v23, v32, v22
	v_mul_f32_e32 v22, v33, v22
	v_mul_f32_e32 v22, v22, v14
	v_mul_f32_e32 v21, v23, v21
	ds_bpermute_b32 v23, v42, v22
	v_cvt_pk_bf16_f32 v20, v20, s0
	s_mov_b32 s0, 0x36000000
	v_add_co_u32_e64 v18, s[0:1], s0, v18
	s_waitcnt lgkmcnt(0)
	v_mul_f32_e32 v23, v43, v23
	v_cndmask_b32_e64 v23, v23, -v23, vcc
	v_addc_co_u32_e64 v19, s[0:1], 0, v19, s[0:1]
	v_fmac_f32_e32 v23, v1, v22
	v_mov_b32_e32 v22, v66
	s_nop 0
	global_store_short v[18:19], v20, off
	v_cvt_pk_bf16_f32 v20, v21, s0
	global_store_short v[18:19], v20, off offset:128
	v_cvt_pk_bf16_f32 v20, v23, s0
	global_store_short v[18:19], v20, off offset:256
	v_mov_b32_e32 v20, v67
	s_mov_b32 s0, 0x358637bd
	v_lshlrev_b32_e32 v23, 16, v22
	v_lshlrev_b32_e32 v22, 16, v20
	v_mov_b32_e32 v20, v68
	v_mov_b32_e32 v21, v69
	v_lshlrev_b32_e32 v24, 16, v20
	v_lshlrev_b32_e32 v25, 16, v21
	v_pk_mul_f32 v[20:21], v[24:25], v[24:25]
	s_nop 0
	v_mov_b32_e32 v26, v20
	v_pk_fma_f32 v[26:27], v[22:23], v[22:23], v[26:27]
	v_pk_mov_b32 v[20:21], v[20:21], v[16:17] op_sel:[1,0]
	s_nop 0
	v_pk_add_f32 v[20:21], v[26:27], v[20:21]
	s_nop 1
	v_mov_b32_dpp v27, v21 quad_perm:[1,0,3,2] row_mask:0xf bank_mask:0xf
	v_mov_b32_dpp v26, v20 quad_perm:[1,0,3,2] row_mask:0xf bank_mask:0xf
	s_waitcnt lgkmcnt(0)
	v_pk_add_f32 v[20:21], v[20:21], v[26:27]
	s_nop 1
	v_mov_b32_dpp v27, v21 quad_perm:[2,3,0,1] row_mask:0xf bank_mask:0xf
	v_mov_b32_dpp v26, v20 quad_perm:[2,3,0,1] row_mask:0xf bank_mask:0xf
	s_waitcnt lgkmcnt(0)
	v_pk_add_f32 v[20:21], v[20:21], v[26:27]
	s_nop 1
	v_mov_b32_dpp v27, v21 row_half_mirror row_mask:0xf bank_mask:0xf
	v_mov_b32_dpp v26, v20 row_half_mirror row_mask:0xf bank_mask:0xf
	s_waitcnt lgkmcnt(0)
	v_pk_add_f32 v[20:21], v[20:21], v[26:27]
	s_nop 1
	v_mov_b32_dpp v27, v21 row_mirror row_mask:0xf bank_mask:0xf
	v_mov_b32_dpp v26, v20 row_mirror row_mask:0xf bank_mask:0xf
	s_waitcnt lgkmcnt(0)
	v_pk_add_f32 v[20:21], v[20:21], v[26:27]
	v_mov_b32_e32 v27, v21
	v_mov_b32_e32 v26, v20
	s_nop 1
	v_permlane16_swap_b32 v21, v27
	v_permlane16_swap_b32 v20, v26
	s_waitcnt lgkmcnt(0)
	v_pk_add_f32 v[20:21], v[20:21], v[26:27]
	v_mov_b32_e32 v27, v21
	v_mov_b32_e32 v26, v20
	s_nop 1
	v_permlane32_swap_b32 v21, v27
	v_permlane32_swap_b32 v20, v26
	s_waitcnt lgkmcnt(0)
	v_pk_add_f32 v[26:27], v[20:21], v[26:27]
	v_mov_b64_e32 v[20:21], s[0:1]
	v_pk_fma_f32 v[26:27], v[26:27], s[16:17], v[20:21] op_sel_hi:[1,0,0]
	s_nop 0
	v_mul_f32_e32 v28, 0x4b800000, v27
	v_cmp_gt_f32_e64 s[38:39], s71, v27
	v_cmp_gt_f32_e64 s[0:1], s71, v26
	s_nop 0
	v_cndmask_b32_e64 v27, v27, v28, s[38:39]
	v_rsq_f32_e32 v27, v27
	s_nop 0
	v_mul_f32_e32 v28, 0x45800000, v27
	v_cndmask_b32_e64 v27, v27, v28, s[38:39]
	v_mul_f32_e32 v28, v35, v27
	v_mul_f32_e32 v15, v28, v15
	v_mul_f32_e32 v28, v32, v27
	v_mul_f32_e32 v27, v33, v27
	v_mul_f32_e32 v27, v27, v14
	v_mul_f32_e32 v23, v28, v23
	ds_bpermute_b32 v28, v42, v27
	v_cvt_pk_bf16_f32 v15, v15, s0
	global_store_short v[18:19], v15, off offset:384
	v_cvt_pk_bf16_f32 v15, v23, s0
	global_store_short v[18:19], v15, off offset:512
	s_waitcnt lgkmcnt(0)
; __device__ __forceinline__ float bf2f(unsigned short h) { return __uint_as_float(((unsigned)h) << 16); }
; __device__ __forceinline__ unsigned short f2bf(float f) { return (unsigned short)(cvt_pk_bf16(f, 0.f) & 0xffffu); }
; __device__ __forceinline__ void pass_qk_prep(const Params& P) {
;     ...
;         for (int h = 0; h < 8; ++h) {
;             bf16_t* q = QB + (size_t)t * 1536 + h * 192;
;             float a0 = bf2f(q[lane]), a1 = bf2f(q[64 + lane]), a2 = bf2f(q[128 + lane]);
;             float rs = rsqrtf(wave_sum(a0 * a0 + a1 * a1 + a2 * a2) * (1.f / 192.f) + EPS);
;             a0 *= rs * qn0; a1 *= rs * qn1; a2 *= rs * qn2;
;             float ot = __shfl_xor(a2, 32);
;             float r2 = lane < 32 ? a2 * cs - ot * sn : a2 * cs + ot * sn;
;             q[lane] = f2bf(a0 * QSC); q[64 + lane] = f2bf(a1 * QSC); q[128 + lane] = f2bf(r2 * QSC);
;             const bf16_t* kv = KVR + (size_t)t * 2048 + h * 256;
;             float b0 = bf2f(kv[lane]), b1 = bf2f(kv[64 + lane]), b2 = kpe;
;             rs = rsqrtf(wave_sum(b0 * b0 + b1 * b1 + b2 * b2) * (1.f / 192.f) + EPS);
;             b0 *= rs * kn0; b1 *= rs * kn1; b2 *= rs * kn2;
;             ot = __shfl_xor(b2, 32);
;             r2 = lane < 32 ? b2 * cs - ot * sn : b2 * cs + ot * sn;
;             bf16_t* k = KB + (size_t)t * 1536 + h * 192;
;             k[lane] = f2bf(b0); k[64 + lane] = f2bf(b1); k[128 + lane] = f2bf(r2);
	v_mul_f32_e32 v28, v43, v28
	v_cndmask_b32_e64 v28, v28, -v28, vcc
	v_fmac_f32_e32 v28, v1, v27
	v_cvt_pk_bf16_f32 v15, v28, s0
	global_store_short v[18:19], v15, off offset:640
	v_mul_f32_e32 v15, 0x4b800000, v26
	v_cndmask_b32_e64 v15, v26, v15, s[0:1]
	v_rsq_f32_e32 v15, v15
	s_nop 0
	v_mul_f32_e32 v23, 0x45800000, v15
	v_cndmask_b32_e64 v15, v15, v23, s[0:1]
	v_mul_f32_e32 v23, v30, v15
	v_mul_f32_e32 v23, v23, v24
	v_mul_f32_e32 v24, v31, v15
	v_mul_f32_e32 v15, v34, v15
	v_mul_f32_e32 v15, v15, v25
	v_mul_f32_e32 v22, v24, v22
	ds_bpermute_b32 v24, v42, v15
	s_waitcnt lgkmcnt(0)
	v_mul_f32_e32 v24, v43, v24
	v_cndmask_b32_e64 v24, v24, -v24, vcc
	v_fmac_f32_e32 v24, v1, v15
	v_mul_f32_e32 v15, 0x3dd53b94, v23
	v_cvt_pk_bf16_f32 v15, v15, s0
	global_store_short v[10:11], v15, off offset:768
	v_mul_f32_e32 v15, 0x3dd53b94, v22
	v_cvt_pk_bf16_f32 v15, v15, s0
	global_store_short v[10:11], v15, off offset:896
	v_mul_f32_e32 v15, 0x3dd53b94, v24
	v_cvt_pk_bf16_f32 v15, v15, s0
	global_store_short v[10:11], v15, off offset:1024
	v_mov_b32_e32 v15, v70
	s_nop 0
	v_mov_b32_e32 v22, v71
	v_lshlrev_b32_e32 v23, 16, v22
	v_lshlrev_b32_e32 v22, 16, v15
	v_mov_b32_e32 v15, v72
	v_mov_b32_e32 v27, v73
	v_mov_b32_e32 v28, v74
	v_pk_mul_f32 v[24:25], v[22:23], v[22:23]
	v_lshlrev_b32_e32 v15, 16, v15
	v_lshlrev_b32_e32 v29, 16, v28
	v_lshlrev_b32_e32 v28, 16, v27
	v_pk_mul_f32 v[44:45], v[28:29], v[28:29]
	v_mul_f32_e32 v26, v15, v15
	v_mov_b32_e32 v46, v44
	v_mov_b32_e32 v47, v24
	v_mov_b32_e32 v27, v25
	v_pk_add_f32 v[24:25], v[46:47], v[26:27]
	v_pk_mov_b32 v[26:27], v[44:45], v[16:17] op_sel:[1,0]
	s_nop 0
	v_pk_add_f32 v[24:25], v[24:25], v[26:27]
	s_nop 1
	v_mov_b32_dpp v27, v25 quad_perm:[1,0,3,2] row_mask:0xf bank_mask:0xf
	v_mov_b32_dpp v26, v24 quad_perm:[1,0,3,2] row_mask:0xf bank_mask:0xf
	s_waitcnt lgkmcnt(0)
	v_pk_add_f32 v[24:25], v[24:25], v[26:27]
	s_nop 1
	v_mov_b32_dpp v27, v25 quad_perm:[2,3,0,1] row_mask:0xf bank_mask:0xf
	v_mov_b32_dpp v26, v24 quad_perm:[2,3,0,1] row_mask:0xf bank_mask:0xf
	s_waitcnt lgkmcnt(0)
	v_pk_add_f32 v[24:25], v[24:25], v[26:27]
	s_nop 1
	v_mov_b32_dpp v27, v25 row_half_mirror row_mask:0xf bank_mask:0xf
	v_mov_b32_dpp v26, v24 row_half_mirror row_mask:0xf bank_mask:0xf
	s_waitcnt lgkmcnt(0)
	v_pk_add_f32 v[24:25], v[24:25], v[26:27]
	s_nop 1
	v_mov_b32_dpp v27, v25 row_mirror row_mask:0xf bank_mask:0xf
	v_mov_b32_dpp v26, v24 row_mirror row_mask:0xf bank_mask:0xf
	s_waitcnt lgkmcnt(0)
	v_pk_add_f32 v[24:25], v[24:25], v[26:27]
	v_mov_b32_e32 v27, v25
	v_mov_b32_e32 v26, v24
	s_nop 1
	v_permlane16_swap_b32 v25, v27
	v_permlane16_swap_b32 v24, v26
	s_waitcnt lgkmcnt(0)
	v_pk_add_f32 v[24:25], v[24:25], v[26:27]
	v_mov_b32_e32 v27, v25
	v_mov_b32_e32 v26, v24
	s_nop 1
	v_permlane32_swap_b32 v25, v27
	v_permlane32_swap_b32 v24, v26
	s_waitcnt lgkmcnt(0)
	v_pk_add_f32 v[24:25], v[24:25], v[26:27]
	s_nop 0
	v_pk_fma_f32 v[24:25], v[24:25], s[16:17], v[20:21] op_sel_hi:[1,0,0]
	s_nop 0
	v_mul_f32_e32 v26, 0x4b800000, v25
	v_cmp_gt_f32_e64 s[38:39], s71, v25
	v_cmp_gt_f32_e64 s[0:1], s71, v24
	s_nop 0
	v_cndmask_b32_e64 v25, v25, v26, s[38:39]
	v_rsq_f32_e32 v25, v25
	s_nop 0
	v_mul_f32_e32 v26, 0x45800000, v25
	v_cndmask_b32_e64 v25, v25, v26, s[38:39]
	v_mul_f32_e32 v26, v35, v25
	v_mul_f32_e32 v22, v26, v22
	v_mul_f32_e32 v26, v32, v25
	v_mul_f32_e32 v25, v33, v25
	v_mul_f32_e32 v25, v25, v14
	v_mul_f32_e32 v23, v26, v23
	ds_bpermute_b32 v26, v42, v25
	v_cvt_pk_bf16_f32 v22, v22, s0
	global_store_short v[18:19], v22, off offset:768
	v_cvt_pk_bf16_f32 v22, v23, s0
	global_store_short v[18:19], v22, off offset:896
	s_waitcnt lgkmcnt(0)
	v_mul_f32_e32 v26, v43, v26
	v_cndmask_b32_e64 v26, v26, -v26, vcc
	v_fmac_f32_e32 v26, v1, v25
	v_cvt_pk_bf16_f32 v22, v26, s0
	global_store_short v[18:19], v22, off offset:1024
	v_mul_f32_e32 v22, 0x4b800000, v24
	v_cndmask_b32_e64 v22, v24, v22, s[0:1]
	v_rsq_f32_e32 v22, v22
	s_nop 0
	v_mul_f32_e32 v23, 0x45800000, v22
	v_cndmask_b32_e64 v22, v22, v23, s[0:1]
	v_mul_f32_e32 v23, v30, v22
	v_mul_f32_e32 v24, v31, v22
	v_mul_f32_e32 v22, v34, v22
	v_mul_f32_e32 v22, v22, v29
	v_mul_f32_e32 v15, v24, v15
	ds_bpermute_b32 v24, v42, v22
	v_mul_f32_e32 v15, 0x3dd53b94, v15
	v_mul_f32_e32 v23, v23, v28
	v_cvt_pk_bf16_f32 v15, v15, s0
	global_store_short v[10:11], v15, off offset:1280
	s_waitcnt lgkmcnt(0)
	v_mul_f32_e32 v24, v43, v24
	v_cndmask_b32_e64 v24, v24, -v24, vcc
	v_fmac_f32_e32 v24, v1, v22
	v_mul_f32_e32 v22, 0x3dd53b94, v23
	v_mul_f32_e32 v15, 0x3dd53b94, v24
	v_cvt_pk_bf16_f32 v22, v22, s0
	v_cvt_pk_bf16_f32 v15, v15, s0
	global_store_short v[10:11], v22, off offset:1152
	global_store_short v[10:11], v15, off offset:1408
	v_mov_b32_e32 v15, v75
	s_nop 0
	v_mov_b32_e32 v22, v76
	v_lshlrev_b32_e32 v23, 16, v22
	v_lshlrev_b32_e32 v22, 16, v15
	v_mov_b32_e32 v15, v77
	v_mov_b32_e32 v27, v78
	v_mov_b32_e32 v28, v79
	v_pk_mul_f32 v[24:25], v[22:23], v[22:23]
	v_lshlrev_b32_e32 v15, 16, v15
	v_lshlrev_b32_e32 v29, 16, v28
	v_lshlrev_b32_e32 v28, 16, v27
	v_pk_mul_f32 v[44:45], v[28:29], v[28:29]
	v_mul_f32_e32 v26, v15, v15
	v_mov_b32_e32 v46, v44
	v_mov_b32_e32 v47, v24
	v_mov_b32_e32 v27, v25
	v_pk_add_f32 v[24:25], v[46:47], v[26:27]
	v_pk_mov_b32 v[26:27], v[44:45], v[16:17] op_sel:[1,0]
	s_nop 0
	v_pk_add_f32 v[24:25], v[24:25], v[26:27]
	s_nop 1
	v_mov_b32_dpp v27, v25 quad_perm:[1,0,3,2] row_mask:0xf bank_mask:0xf
	v_mov_b32_dpp v26, v24 quad_perm:[1,0,3,2] row_mask:0xf bank_mask:0xf
	s_waitcnt lgkmcnt(0)
	v_pk_add_f32 v[24:25], v[24:25], v[26:27]
	s_nop 1
	v_mov_b32_dpp v27, v25 quad_perm:[2,3,0,1] row_mask:0xf bank_mask:0xf
	v_mov_b32_dpp v26, v24 quad_perm:[2,3,0,1] row_mask:0xf bank_mask:0xf
	s_waitcnt lgkmcnt(0)
; __device__ __forceinline__ float bf2f(unsigned short h) { return __uint_as_float(((unsigned)h) << 16); }
; __device__ __forceinline__ unsigned short f2bf(float f) { return (unsigned short)(cvt_pk_bf16(f, 0.f) & 0xffffu); }
; __device__ __forceinline__ void pass_qk_prep(const Params& P) {
;     ...
;         for (int h = 0; h < 8; ++h) {
;             bf16_t* q = QB + (size_t)t * 1536 + h * 192;
;             float a0 = bf2f(q[lane]), a1 = bf2f(q[64 + lane]), a2 = bf2f(q[128 + lane]);
;             float rs = rsqrtf(wave_sum(a0 * a0 + a1 * a1 + a2 * a2) * (1.f / 192.f) + EPS);
;             a0 *= rs * qn0; a1 *= rs * qn1; a2 *= rs * qn2;
;             float ot = __shfl_xor(a2, 32);
;             float r2 = lane < 32 ? a2 * cs - ot * sn : a2 * cs + ot * sn;
;             q[lane] = f2bf(a0 * QSC); q[64 + lane] = f2bf(a1 * QSC); q[128 + lane] = f2bf(r2 * QSC);
;             const bf16_t* kv = KVR + (size_t)t * 2048 + h * 256;
;             float b0 = bf2f(kv[lane]), b1 = bf2f(kv[64 + lane]), b2 = kpe;
;             rs = rsqrtf(wave_sum(b0 * b0 + b1 * b1 + b2 * b2) * (1.f / 192.f) + EPS);
;             b0 *= rs * kn0; b1 *= rs * kn1; b2 *= rs * kn2;
;             ot = __shfl_xor(b2, 32);
;             r2 = lane < 32 ? b2 * cs - ot * sn : b2 * cs + ot * sn;
;             bf16_t* k = KB + (size_t)t * 1536 + h * 192;
;             k[lane] = f2bf(b0); k[64 + lane] = f2bf(b1); k[128 + lane] = f2bf(r2);
	v_pk_add_f32 v[24:25], v[24:25], v[26:27]
	s_nop 1
	v_mov_b32_dpp v27, v25 row_half_mirror row_mask:0xf bank_mask:0xf
	v_mov_b32_dpp v26, v24 row_half_mirror row_mask:0xf bank_mask:0xf
	s_waitcnt lgkmcnt(0)
	v_pk_add_f32 v[24:25], v[24:25], v[26:27]
	s_nop 1
	v_mov_b32_dpp v27, v25 row_mirror row_mask:0xf bank_mask:0xf
	v_mov_b32_dpp v26, v24 row_mirror row_mask:0xf bank_mask:0xf
	s_waitcnt lgkmcnt(0)
	v_pk_add_f32 v[24:25], v[24:25], v[26:27]
	v_mov_b32_e32 v27, v25
	v_mov_b32_e32 v26, v24
	s_nop 1
	v_permlane16_swap_b32 v25, v27
	v_permlane16_swap_b32 v24, v26
	s_waitcnt lgkmcnt(0)
	v_pk_add_f32 v[24:25], v[24:25], v[26:27]
	v_mov_b32_e32 v27, v25
	v_mov_b32_e32 v26, v24
	s_nop 1
	v_permlane32_swap_b32 v25, v27
	v_permlane32_swap_b32 v24, v26
	s_waitcnt lgkmcnt(0)
	v_pk_add_f32 v[24:25], v[24:25], v[26:27]
	s_nop 0
	v_pk_fma_f32 v[24:25], v[24:25], s[16:17], v[20:21] op_sel_hi:[1,0,0]
	s_nop 0
	v_mul_f32_e32 v26, 0x4b800000, v25
	v_cmp_gt_f32_e64 s[38:39], s71, v25
	v_cmp_gt_f32_e64 s[0:1], s71, v24
	s_nop 0
	v_cndmask_b32_e64 v25, v25, v26, s[38:39]
	v_rsq_f32_e32 v25, v25
	s_nop 0
	v_mul_f32_e32 v26, 0x45800000, v25
	v_cndmask_b32_e64 v25, v25, v26, s[38:39]
	v_mul_f32_e32 v26, v35, v25
	v_mul_f32_e32 v22, v26, v22
	v_mul_f32_e32 v26, v32, v25
	v_mul_f32_e32 v25, v33, v25
	v_mul_f32_e32 v25, v25, v14
	v_mul_f32_e32 v23, v26, v23
	ds_bpermute_b32 v26, v42, v25
	v_cvt_pk_bf16_f32 v22, v22, s0
	global_store_short v[18:19], v22, off offset:1152
	v_cvt_pk_bf16_f32 v22, v23, s0
	global_store_short v[18:19], v22, off offset:1280
	s_waitcnt lgkmcnt(0)
	v_mul_f32_e32 v26, v43, v26
	v_cndmask_b32_e64 v26, v26, -v26, vcc
	v_fmac_f32_e32 v26, v1, v25
	v_cvt_pk_bf16_f32 v22, v26, s0
	global_store_short v[18:19], v22, off offset:1408
	v_mul_f32_e32 v22, 0x4b800000, v24
	v_cndmask_b32_e64 v22, v24, v22, s[0:1]
	v_rsq_f32_e32 v22, v22
	s_nop 0
	v_mul_f32_e32 v23, 0x45800000, v22
	v_cndmask_b32_e64 v22, v22, v23, s[0:1]
	v_mul_f32_e32 v23, v30, v22
	v_mul_f32_e32 v24, v31, v22
	v_mul_f32_e32 v22, v34, v22
	v_mul_f32_e32 v22, v22, v29
	v_mul_f32_e32 v15, v24, v15
	ds_bpermute_b32 v24, v42, v22
	v_mul_f32_e32 v15, 0x3dd53b94, v15
	v_mul_f32_e32 v23, v23, v28
	v_cvt_pk_bf16_f32 v15, v15, s0
	global_store_short v[10:11], v15, off offset:1664
	s_waitcnt lgkmcnt(0)
	v_mul_f32_e32 v24, v43, v24
	v_cndmask_b32_e64 v24, v24, -v24, vcc
	v_fmac_f32_e32 v24, v1, v22
	v_mul_f32_e32 v22, 0x3dd53b94, v23
	v_mul_f32_e32 v15, 0x3dd53b94, v24
	v_cvt_pk_bf16_f32 v22, v22, s0
	v_cvt_pk_bf16_f32 v15, v15, s0
	global_store_short v[10:11], v22, off offset:1536
	global_store_short v[10:11], v15, off offset:1792
	v_mov_b32_e32 v15, v80
	s_nop 0
	v_mov_b32_e32 v22, v81
	v_lshlrev_b32_e32 v23, 16, v22
	v_lshlrev_b32_e32 v22, 16, v15
	v_mov_b32_e32 v15, v82
	v_mov_b32_e32 v27, v83
	v_mov_b32_e32 v28, v84
	v_pk_mul_f32 v[24:25], v[22:23], v[22:23]
	v_lshlrev_b32_e32 v15, 16, v15
	v_lshlrev_b32_e32 v29, 16, v28
	v_lshlrev_b32_e32 v28, 16, v27
	v_pk_mul_f32 v[44:45], v[28:29], v[28:29]
	v_mul_f32_e32 v26, v15, v15
	v_mov_b32_e32 v46, v44
	v_mov_b32_e32 v47, v24
	v_mov_b32_e32 v27, v25
	v_pk_add_f32 v[24:25], v[46:47], v[26:27]
	v_pk_mov_b32 v[26:27], v[44:45], v[16:17] op_sel:[1,0]
	s_nop 0
	v_pk_add_f32 v[24:25], v[24:25], v[26:27]
	s_nop 1
	v_mov_b32_dpp v27, v25 quad_perm:[1,0,3,2] row_mask:0xf bank_mask:0xf
	v_mov_b32_dpp v26, v24 quad_perm:[1,0,3,2] row_mask:0xf bank_mask:0xf
	s_waitcnt lgkmcnt(0)
	v_pk_add_f32 v[24:25], v[24:25], v[26:27]
	s_nop 1
	v_mov_b32_dpp v27, v25 quad_perm:[2,3,0,1] row_mask:0xf bank_mask:0xf
	v_mov_b32_dpp v26, v24 quad_perm:[2,3,0,1] row_mask:0xf bank_mask:0xf
	s_waitcnt lgkmcnt(0)
	v_pk_add_f32 v[24:25], v[24:25], v[26:27]
	s_nop 1
	v_mov_b32_dpp v27, v25 row_half_mirror row_mask:0xf bank_mask:0xf
	v_mov_b32_dpp v26, v24 row_half_mirror row_mask:0xf bank_mask:0xf
	s_waitcnt lgkmcnt(0)
	v_pk_add_f32 v[24:25], v[24:25], v[26:27]
	s_nop 1
	v_mov_b32_dpp v27, v25 row_mirror row_mask:0xf bank_mask:0xf
	v_mov_b32_dpp v26, v24 row_mirror row_mask:0xf bank_mask:0xf
	s_waitcnt lgkmcnt(0)
	v_pk_add_f32 v[24:25], v[24:25], v[26:27]
	v_mov_b32_e32 v27, v25
	v_mov_b32_e32 v26, v24
	s_nop 1
	v_permlane16_swap_b32 v25, v27
	v_permlane16_swap_b32 v24, v26
	s_waitcnt lgkmcnt(0)
	v_pk_add_f32 v[24:25], v[24:25], v[26:27]
	v_mov_b32_e32 v27, v25
	v_mov_b32_e32 v26, v24
	s_nop 1
	v_permlane32_swap_b32 v25, v27
	v_permlane32_swap_b32 v24, v26
	s_waitcnt lgkmcnt(0)
	v_pk_add_f32 v[24:25], v[24:25], v[26:27]
	s_nop 0
	v_pk_fma_f32 v[24:25], v[24:25], s[16:17], v[20:21] op_sel_hi:[1,0,0]
	s_nop 0
	v_mul_f32_e32 v26, 0x4b800000, v25
	v_cmp_gt_f32_e64 s[38:39], s71, v25
	v_cmp_gt_f32_e64 s[0:1], s71, v24
	s_nop 0
	v_cndmask_b32_e64 v25, v25, v26, s[38:39]
	v_rsq_f32_e32 v25, v25
	s_nop 0
	v_mul_f32_e32 v26, 0x45800000, v25
	v_cndmask_b32_e64 v25, v25, v26, s[38:39]
	v_mul_f32_e32 v26, v35, v25
	v_mul_f32_e32 v22, v26, v22
	v_mul_f32_e32 v26, v32, v25
	v_mul_f32_e32 v25, v33, v25
	v_mul_f32_e32 v25, v25, v14
	v_mul_f32_e32 v23, v26, v23
	ds_bpermute_b32 v26, v42, v25
	v_cvt_pk_bf16_f32 v22, v22, s0
	global_store_short v[18:19], v22, off offset:1536
	v_cvt_pk_bf16_f32 v22, v23, s0
	global_store_short v[18:19], v22, off offset:1664
	s_waitcnt lgkmcnt(0)
	v_mul_f32_e32 v26, v43, v26
	v_cndmask_b32_e64 v26, v26, -v26, vcc
	v_fmac_f32_e32 v26, v1, v25
	v_cvt_pk_bf16_f32 v22, v26, s0
	global_store_short v[18:19], v22, off offset:1792
	v_mul_f32_e32 v22, 0x4b800000, v24
	v_cndmask_b32_e64 v22, v24, v22, s[0:1]
	v_rsq_f32_e32 v22, v22
	s_nop 0
	v_mul_f32_e32 v23, 0x45800000, v22
	v_cndmask_b32_e64 v22, v22, v23, s[0:1]
	v_mul_f32_e32 v23, v30, v22
	v_mul_f32_e32 v24, v31, v22
	v_mul_f32_e32 v22, v34, v22
	v_mul_f32_e32 v22, v22, v29
	v_mul_f32_e32 v15, v24, v15
	ds_bpermute_b32 v24, v42, v22
	v_mul_f32_e32 v15, 0x3dd53b94, v15
	v_mul_f32_e32 v23, v23, v28
	v_cvt_pk_bf16_f32 v15, v15, s0
	global_store_short v[10:11], v15, off offset:2048
	s_waitcnt lgkmcnt(0)
; __device__ __forceinline__ float bf2f(unsigned short h) { return __uint_as_float(((unsigned)h) << 16); }
; __device__ __forceinline__ unsigned short f2bf(float f) { return (unsigned short)(cvt_pk_bf16(f, 0.f) & 0xffffu); }
; __device__ __forceinline__ void pass_qk_prep(const Params& P) {
;     ...
;         for (int h = 0; h < 8; ++h) {
;             bf16_t* q = QB + (size_t)t * 1536 + h * 192;
;             float a0 = bf2f(q[lane]), a1 = bf2f(q[64 + lane]), a2 = bf2f(q[128 + lane]);
;             float rs = rsqrtf(wave_sum(a0 * a0 + a1 * a1 + a2 * a2) * (1.f / 192.f) + EPS);
;             a0 *= rs * qn0; a1 *= rs * qn1; a2 *= rs * qn2;
;             float ot = __shfl_xor(a2, 32);
;             float r2 = lane < 32 ? a2 * cs - ot * sn : a2 * cs + ot * sn;
;             q[lane] = f2bf(a0 * QSC); q[64 + lane] = f2bf(a1 * QSC); q[128 + lane] = f2bf(r2 * QSC);
;             const bf16_t* kv = KVR + (size_t)t * 2048 + h * 256;
;             float b0 = bf2f(kv[lane]), b1 = bf2f(kv[64 + lane]), b2 = kpe;
;             rs = rsqrtf(wave_sum(b0 * b0 + b1 * b1 + b2 * b2) * (1.f / 192.f) + EPS);
;             b0 *= rs * kn0; b1 *= rs * kn1; b2 *= rs * kn2;
;             ot = __shfl_xor(b2, 32);
;             r2 = lane < 32 ? b2 * cs - ot * sn : b2 * cs + ot * sn;
;             bf16_t* k = KB + (size_t)t * 1536 + h * 192;
;             k[lane] = f2bf(b0); k[64 + lane] = f2bf(b1); k[128 + lane] = f2bf(r2);
	v_mul_f32_e32 v24, v43, v24
	v_cndmask_b32_e64 v24, v24, -v24, vcc
	v_fmac_f32_e32 v24, v1, v22
	v_mul_f32_e32 v22, 0x3dd53b94, v23
	v_mul_f32_e32 v15, 0x3dd53b94, v24
	v_cvt_pk_bf16_f32 v22, v22, s0
	v_cvt_pk_bf16_f32 v15, v15, s0
	global_store_short v[10:11], v22, off offset:1920
	global_store_short v[10:11], v15, off offset:2176
	v_mov_b32_e32 v15, v85
	s_nop 0
	v_mov_b32_e32 v22, v86
	v_lshlrev_b32_e32 v23, 16, v22
	v_lshlrev_b32_e32 v22, 16, v15
	v_mov_b32_e32 v15, v87
	v_mov_b32_e32 v27, v88
	v_mov_b32_e32 v28, v89
	v_pk_mul_f32 v[24:25], v[22:23], v[22:23]
	v_lshlrev_b32_e32 v15, 16, v15
	v_lshlrev_b32_e32 v29, 16, v28
	v_lshlrev_b32_e32 v28, 16, v27
	v_pk_mul_f32 v[44:45], v[28:29], v[28:29]
	v_mul_f32_e32 v26, v15, v15
	v_mov_b32_e32 v46, v44
	v_mov_b32_e32 v47, v24
	v_mov_b32_e32 v27, v25
	v_pk_add_f32 v[24:25], v[46:47], v[26:27]
	v_pk_mov_b32 v[26:27], v[44:45], v[16:17] op_sel:[1,0]
	s_nop 0
	v_pk_add_f32 v[24:25], v[24:25], v[26:27]
	s_nop 1
	v_mov_b32_dpp v27, v25 quad_perm:[1,0,3,2] row_mask:0xf bank_mask:0xf
	v_mov_b32_dpp v26, v24 quad_perm:[1,0,3,2] row_mask:0xf bank_mask:0xf
	s_waitcnt lgkmcnt(0)
	v_pk_add_f32 v[24:25], v[24:25], v[26:27]
	s_nop 1
	v_mov_b32_dpp v27, v25 quad_perm:[2,3,0,1] row_mask:0xf bank_mask:0xf
	v_mov_b32_dpp v26, v24 quad_perm:[2,3,0,1] row_mask:0xf bank_mask:0xf
	s_waitcnt lgkmcnt(0)
	v_pk_add_f32 v[24:25], v[24:25], v[26:27]
	s_nop 1
	v_mov_b32_dpp v27, v25 row_half_mirror row_mask:0xf bank_mask:0xf
	v_mov_b32_dpp v26, v24 row_half_mirror row_mask:0xf bank_mask:0xf
	s_waitcnt lgkmcnt(0)
	v_pk_add_f32 v[24:25], v[24:25], v[26:27]
	s_nop 1
	v_mov_b32_dpp v27, v25 row_mirror row_mask:0xf bank_mask:0xf
	v_mov_b32_dpp v26, v24 row_mirror row_mask:0xf bank_mask:0xf
	s_waitcnt lgkmcnt(0)
	v_pk_add_f32 v[24:25], v[24:25], v[26:27]
	v_mov_b32_e32 v27, v25
	v_mov_b32_e32 v26, v24
	s_nop 1
	v_permlane16_swap_b32 v25, v27
	v_permlane16_swap_b32 v24, v26
	s_waitcnt lgkmcnt(0)
	v_pk_add_f32 v[24:25], v[24:25], v[26:27]
	v_mov_b32_e32 v27, v25
	v_mov_b32_e32 v26, v24
	s_nop 1
	v_permlane32_swap_b32 v25, v27
	v_permlane32_swap_b32 v24, v26
	s_waitcnt lgkmcnt(0)
	v_pk_add_f32 v[24:25], v[24:25], v[26:27]
	s_nop 0
	v_pk_fma_f32 v[24:25], v[24:25], s[16:17], v[20:21] op_sel_hi:[1,0,0]
	s_nop 0
	v_mul_f32_e32 v26, 0x4b800000, v25
	v_cmp_gt_f32_e64 s[38:39], s71, v25
	v_cmp_gt_f32_e64 s[0:1], s71, v24
	s_nop 0
	v_cndmask_b32_e64 v25, v25, v26, s[38:39]
	v_rsq_f32_e32 v25, v25
	s_nop 0
	v_mul_f32_e32 v26, 0x45800000, v25
	v_cndmask_b32_e64 v25, v25, v26, s[38:39]
	v_mul_f32_e32 v26, v35, v25
	v_mul_f32_e32 v22, v26, v22
	v_mul_f32_e32 v26, v32, v25
	v_mul_f32_e32 v25, v33, v25
	v_mul_f32_e32 v25, v25, v14
	v_mul_f32_e32 v23, v26, v23
	ds_bpermute_b32 v26, v42, v25
	v_cvt_pk_bf16_f32 v22, v22, s0
	global_store_short v[18:19], v22, off offset:1920
	v_cvt_pk_bf16_f32 v22, v23, s0
	global_store_short v[18:19], v22, off offset:2048
	s_waitcnt lgkmcnt(0)
	v_mul_f32_e32 v26, v43, v26
	v_cndmask_b32_e64 v26, v26, -v26, vcc
	v_fmac_f32_e32 v26, v1, v25
	v_cvt_pk_bf16_f32 v22, v26, s0
	global_store_short v[18:19], v22, off offset:2176
	v_mul_f32_e32 v22, 0x4b800000, v24
	v_cndmask_b32_e64 v22, v24, v22, s[0:1]
	v_rsq_f32_e32 v22, v22
	s_nop 0
	v_mul_f32_e32 v23, 0x45800000, v22
	v_cndmask_b32_e64 v22, v22, v23, s[0:1]
	v_mul_f32_e32 v23, v30, v22
	v_mul_f32_e32 v24, v31, v22
	v_mul_f32_e32 v22, v34, v22
	v_mul_f32_e32 v22, v22, v29
	v_mul_f32_e32 v15, v24, v15
	ds_bpermute_b32 v24, v42, v22
	v_mul_f32_e32 v15, 0x3dd53b94, v15
	v_mul_f32_e32 v23, v23, v28
	v_cvt_pk_bf16_f32 v15, v15, s0
	global_store_short v[10:11], v15, off offset:2432
	s_waitcnt lgkmcnt(0)
	v_mul_f32_e32 v24, v43, v24
	v_cndmask_b32_e64 v24, v24, -v24, vcc
	v_fmac_f32_e32 v24, v1, v22
	v_mul_f32_e32 v22, 0x3dd53b94, v23
	v_mul_f32_e32 v15, 0x3dd53b94, v24
	v_cvt_pk_bf16_f32 v22, v22, s0
	v_cvt_pk_bf16_f32 v15, v15, s0
	global_store_short v[10:11], v22, off offset:2304
	global_store_short v[10:11], v15, off offset:2560
	v_mov_b32_e32 v15, v90
	s_nop 0
	v_mov_b32_e32 v22, v91
	v_lshlrev_b32_e32 v23, 16, v22
	v_lshlrev_b32_e32 v22, 16, v15
	v_mov_b32_e32 v15, v92
	v_mov_b32_e32 v27, v93
	v_mov_b32_e32 v28, v94
	v_pk_mul_f32 v[24:25], v[22:23], v[22:23]
	v_lshlrev_b32_e32 v15, 16, v15
	v_lshlrev_b32_e32 v29, 16, v28
	v_lshlrev_b32_e32 v28, 16, v27
	v_pk_mul_f32 v[44:45], v[28:29], v[28:29]
	v_mul_f32_e32 v26, v15, v15
	v_mov_b32_e32 v46, v44
	v_mov_b32_e32 v47, v24
	v_mov_b32_e32 v27, v25
	v_pk_add_f32 v[24:25], v[46:47], v[26:27]
	v_pk_mov_b32 v[26:27], v[44:45], v[16:17] op_sel:[1,0]
	s_nop 0
	v_pk_add_f32 v[24:25], v[24:25], v[26:27]
	s_nop 1
	v_mov_b32_dpp v27, v25 quad_perm:[1,0,3,2] row_mask:0xf bank_mask:0xf
	v_mov_b32_dpp v26, v24 quad_perm:[1,0,3,2] row_mask:0xf bank_mask:0xf
	s_waitcnt lgkmcnt(0)
; __device__ __forceinline__ float bf2f(unsigned short h) { return __uint_as_float(((unsigned)h) << 16); }
; __device__ __forceinline__ unsigned short f2bf(float f) { return (unsigned short)(cvt_pk_bf16(f, 0.f) & 0xffffu); }
; __device__ __forceinline__ void pass_qk_prep(const Params& P) {
;     ...
;         for (int h = 0; h < 8; ++h) {
;             bf16_t* q = QB + (size_t)t * 1536 + h * 192;
;             float a0 = bf2f(q[lane]), a1 = bf2f(q[64 + lane]), a2 = bf2f(q[128 + lane]);
;             float rs = rsqrtf(wave_sum(a0 * a0 + a1 * a1 + a2 * a2) * (1.f / 192.f) + EPS);
;             a0 *= rs * qn0; a1 *= rs * qn1; a2 *= rs * qn2;
;             float ot = __shfl_xor(a2, 32);
;             float r2 = lane < 32 ? a2 * cs - ot * sn : a2 * cs + ot * sn;
;             q[lane] = f2bf(a0 * QSC); q[64 + lane] = f2bf(a1 * QSC); q[128 + lane] = f2bf(r2 * QSC);
;             const bf16_t* kv = KVR + (size_t)t * 2048 + h * 256;
;             float b0 = bf2f(kv[lane]), b1 = bf2f(kv[64 + lane]), b2 = kpe;
;             rs = rsqrtf(wave_sum(b0 * b0 + b1 * b1 + b2 * b2) * (1.f / 192.f) + EPS);
;             b0 *= rs * kn0; b1 *= rs * kn1; b2 *= rs * kn2;
;             ot = __shfl_xor(b2, 32);
;             r2 = lane < 32 ? b2 * cs - ot * sn : b2 * cs + ot * sn;
;             bf16_t* k = KB + (size_t)t * 1536 + h * 192;
;             k[lane] = f2bf(b0); k[64 + lane] = f2bf(b1); k[128 + lane] = f2bf(r2);
;         }
;     }
	v_pk_add_f32 v[24:25], v[24:25], v[26:27]
	s_nop 1
	v_mov_b32_dpp v27, v25 quad_perm:[2,3,0,1] row_mask:0xf bank_mask:0xf
	v_mov_b32_dpp v26, v24 quad_perm:[2,3,0,1] row_mask:0xf bank_mask:0xf
	s_waitcnt lgkmcnt(0)
	v_pk_add_f32 v[24:25], v[24:25], v[26:27]
	s_nop 1
	v_mov_b32_dpp v27, v25 row_half_mirror row_mask:0xf bank_mask:0xf
	v_mov_b32_dpp v26, v24 row_half_mirror row_mask:0xf bank_mask:0xf
	s_waitcnt lgkmcnt(0)
	v_pk_add_f32 v[24:25], v[24:25], v[26:27]
	s_nop 1
	v_mov_b32_dpp v27, v25 row_mirror row_mask:0xf bank_mask:0xf
	v_mov_b32_dpp v26, v24 row_mirror row_mask:0xf bank_mask:0xf
	s_waitcnt lgkmcnt(0)
	v_pk_add_f32 v[24:25], v[24:25], v[26:27]
	v_mov_b32_e32 v27, v25
	v_mov_b32_e32 v26, v24
	s_nop 1
	v_permlane16_swap_b32 v25, v27
	v_permlane16_swap_b32 v24, v26
	s_waitcnt lgkmcnt(0)
	v_pk_add_f32 v[24:25], v[24:25], v[26:27]
	v_mov_b32_e32 v27, v25
	v_mov_b32_e32 v26, v24
	s_nop 1
	v_permlane32_swap_b32 v25, v27
	v_permlane32_swap_b32 v24, v26
	s_waitcnt lgkmcnt(0)
	v_pk_add_f32 v[24:25], v[24:25], v[26:27]
	s_nop 0
	v_pk_fma_f32 v[20:21], v[24:25], s[16:17], v[20:21] op_sel_hi:[1,0,0]
	s_nop 0
	v_mul_f32_e32 v17, 0x4b800000, v21
	v_cmp_gt_f32_e64 s[38:39], s71, v21
	v_cmp_gt_f32_e64 s[0:1], s71, v20
	s_nop 0
	v_cndmask_b32_e64 v17, v21, v17, s[38:39]
	v_rsq_f32_e32 v17, v17
	s_nop 0
	v_mul_f32_e32 v21, 0x45800000, v17
	v_cndmask_b32_e64 v17, v17, v21, s[38:39]
	v_mul_f32_e32 v21, v35, v17
	v_mul_f32_e32 v21, v21, v22
	v_mul_f32_e32 v22, v32, v17
	v_mul_f32_e32 v17, v33, v17
	v_mul_f32_e32 v17, v17, v14
	v_mul_f32_e32 v22, v22, v23
	ds_bpermute_b32 v23, v42, v17
	s_waitcnt lgkmcnt(0)
	v_mul_f32_e32 v23, v43, v23
	v_cndmask_b32_e64 v23, v23, -v23, vcc
	v_fmac_f32_e32 v23, v1, v17
	v_cvt_pk_bf16_f32 v17, v21, s0
	global_store_short v[18:19], v17, off offset:2304
	v_cvt_pk_bf16_f32 v17, v22, s0
	global_store_short v[18:19], v17, off offset:2432
	v_cvt_pk_bf16_f32 v17, v23, s0
	global_store_short v[18:19], v17, off offset:2560
	v_mul_f32_e32 v17, 0x4b800000, v20
	v_cndmask_b32_e64 v17, v20, v17, s[0:1]
	v_rsq_f32_e32 v17, v17
	s_nop 0
	v_mul_f32_e32 v20, 0x45800000, v17
	v_cndmask_b32_e64 v17, v17, v20, s[0:1]
	v_mul_f32_e32 v20, v30, v17
	v_mul_f32_e32 v21, v31, v17
	v_mul_f32_e32 v17, v34, v17
	v_mul_f32_e32 v17, v17, v29
	v_mul_f32_e32 v15, v21, v15
	ds_bpermute_b32 v21, v42, v17
	v_mul_f32_e32 v15, 0x3dd53b94, v15
	v_mul_f32_e32 v20, v20, v28
	v_cvt_pk_bf16_f32 v15, v15, s0
	global_store_short v[10:11], v15, off offset:2816
	s_waitcnt lgkmcnt(0)
	v_mul_f32_e32 v21, v43, v21
	v_cndmask_b32_e64 v21, v21, -v21, vcc
	v_fmac_f32_e32 v21, v1, v17
	v_mul_f32_e32 v17, 0x3dd53b94, v20
	v_mul_f32_e32 v15, 0x3dd53b94, v21
	v_cvt_pk_bf16_f32 v17, v17, s0
	v_cvt_pk_bf16_f32 v15, v15, s0
	global_store_short v[10:11], v17, off offset:2688
	global_store_short v[10:11], v15, off offset:2944
	v_mov_b32_e32 v10, v95
	s_nop 0
	v_mov_b32_e32 v11, v96
	v_lshlrev_b32_e32 v10, 16, v10
	v_lshlrev_b32_e32 v11, 16, v11
	v_pk_mul_f32 v[12:13], v[10:11], v[10:11]
	s_nop 0
	v_add_f32_e32 v12, v12, v13
	v_add_f32_e32 v12, v16, v12
	s_nop 1
	v_mov_b32_dpp v13, v12 quad_perm:[1,0,3,2] row_mask:0xf bank_mask:0xf
	s_waitcnt lgkmcnt(0)
	v_add_f32_e32 v12, v12, v13
	s_nop 1
	v_mov_b32_dpp v13, v12 quad_perm:[2,3,0,1] row_mask:0xf bank_mask:0xf
	s_waitcnt lgkmcnt(0)
	v_add_f32_e32 v12, v12, v13
	s_nop 1
	v_mov_b32_dpp v13, v12 row_half_mirror row_mask:0xf bank_mask:0xf
	s_waitcnt lgkmcnt(0)
	v_add_f32_e32 v12, v12, v13
	s_nop 1
	v_mov_b32_dpp v13, v12 row_mirror row_mask:0xf bank_mask:0xf
	s_waitcnt lgkmcnt(0)
	v_add_f32_e32 v12, v12, v13
	v_mov_b32_e32 v13, v12
	s_nop 1
	v_permlane16_swap_b32 v12, v13
	s_waitcnt lgkmcnt(0)
	v_add_f32_e32 v12, v12, v13
	v_mov_b32_e32 v13, v12
	s_nop 1
	v_permlane32_swap_b32 v12, v13
	s_waitcnt lgkmcnt(0)
	v_add_f32_e32 v12, v12, v13
	v_fmamk_f32 v12, v12, 0x3baaaaab, v203
	v_cmp_gt_f32_e64 s[0:1], s71, v12
	v_mul_f32_e32 v13, 0x4b800000, v12
	s_nop 0
	v_cndmask_b32_e64 v12, v12, v13, s[0:1]
	v_rsq_f32_e32 v12, v12
	s_nop 0
	v_mul_f32_e32 v13, 0x45800000, v12
	v_cndmask_b32_e64 v12, v12, v13, s[0:1]
	v_mul_f32_e32 v13, v35, v12
	v_mul_f32_e32 v10, v13, v10
	v_mul_f32_e32 v13, v32, v12
	v_mul_f32_e32 v12, v33, v12
	v_mul_f32_e32 v12, v12, v14
	v_mul_f32_e32 v11, v13, v11
	ds_bpermute_b32 v13, v42, v12
	s_waitcnt lgkmcnt(0)
	v_mul_f32_e32 v13, v43, v13
	v_cndmask_b32_e64 v13, v13, -v13, vcc
	v_fmac_f32_e32 v13, v1, v12
	v_cvt_pk_bf16_f32 v1, v10, s0
	global_store_short v[18:19], v1, off offset:2688
	v_cvt_pk_bf16_f32 v1, v11, s0
	global_store_short v[18:19], v1, off offset:2816
	v_cvt_pk_bf16_f32 v1, v13, s0
	v_cmp_lt_i32_e64 s[0:1], s15, v0
	s_or_b64 s[20:21], s[0:1], s[20:21]
	global_store_short v[18:19], v1, off offset:2944
	s_andn2_b64 exec, exec, s[20:21]
	s_cbranch_execnz .LBB0_202
